# FFN-up epilogue: cndmask/DPP pairs pipelined over 3 temps, dead inits+nops removed; attention loop re-interleaved, LDS-DMA issue spread
# speedup vs baseline: 1.0164x; 1.0068x over previous
; __device__ __forceinline__ void dattn_unit(LAS unsigned char* lds, const bf16_t* Qp, const bf16_t* Kp, const bf16_t* Vtp, int qb, bf16_t* Op, const float* lq1, const float* lk1, const float* lq2, const float* lk2, const float* subg, float outscale, int tid) {
;     ...
;     const int q15 = qi & 15;
;     const int kx0 = qi * 256 + (((c * 8 + hh) ^ q15) << 4);
;     const int vx = qi * 128 + ((hh ^ ((qi >> 1) & 7)) << 4);
.LBB0_215:
	s_add_i32 s6, s5, 0x4000
	s_and_b32 s6, s6, 0xc000
	s_add_i32 s7, s15, s6
	v_lshl_add_u64 v[208:209], s[74:75], 0, v[206:207]
	s_add_i32 s6, s16, s6
	s_mov_b32 s98, s7
	s_mov_b32 s99, s6
	v_lshl_add_u64 v[210:211], s[74:75], 0, v[80:81]
	s_waitcnt vmcnt(4)
	s_barrier
	v_lshl_add_u64 v[212:213], s[74:75], 0, v[204:205]
	v_lshl_add_u64 v[214:215], s[74:75], 0, v[202:203]
	s_add_i32 s6, s5, 0xffff8000
	s_and_b32 s6, s6, 0x8000
	s_add_i32 s7, s6, 0
	v_add_u32_e32 v0, s7, v230
	ds_read_b128 v[68:71], v0 offset:16384
	ds_read_b128 v[72:75], v0 offset:24576
	v_add_u32_e32 v0, s7, v231
	ds_read_b128 v[76:79], v0 offset:16384
	ds_read_b128 v[162:165], v0 offset:24576
	v_max3_f32 v240, v98, v82, v99
	v_max3_f32 v66, v83, v100, v84
	s_waitcnt lgkmcnt(0)
	v_mfma_f32_32x32x16_bf16 v[146:161], v[68:71], v[190:193], v[114:129]
	v_add_u32_e32 v0, s7, v229
	v_max3_f32 v240, v240, v101, v85
	v_max3_f32 v66, v66, v102, v86
	v_mfma_f32_32x32x16_bf16 v[130:145], v[72:75], v[190:193], v[114:129]
	s_mov_b32 m0, s98
	v_lshl_add_u64 v[242:243], v[208:209], 0, s[36:37]
	global_load_lds_dwordx4 v[242:243], off
	ds_read_b128 v[68:71], v0 offset:16384
	ds_read_b128 v[72:75], v0 offset:24576
	v_add_u32_e32 v0, s7, v233
	v_max3_f32 v240, v240, v103, v87
	v_max3_f32 v66, v66, v104, v88
	v_mfma_f32_32x32x16_bf16 v[146:161], v[76:79], v[186:189], v[146:161]
	ds_read_b128 v[76:79], v0 offset:16384
	ds_read_b128 v[166:169], v0 offset:24576
	v_max3_f32 v240, v240, v105, v89
	v_max3_f32 v66, v66, v106, v90
	v_mfma_f32_32x32x16_bf16 v[130:145], v[162:165], v[186:189], v[130:145]
	s_waitcnt lgkmcnt(0)
	v_max3_f32 v240, v240, v107, v91
	v_max3_f32 v66, v66, v108, v92
	v_mfma_f32_32x32x16_bf16 v[146:161], v[68:71], v[182:185], v[146:161]
	v_max3_f32 v240, v240, v109, v93
	v_max3_f32 v66, v66, v110, v94
	v_mfma_f32_32x32x16_bf16 v[130:145], v[72:75], v[182:185], v[130:145]
	s_mov_b32 m0, s99
	v_lshl_add_u64 v[242:243], v[210:211], 0, s[58:59]
	global_load_lds_dwordx4 v[242:243], off
	v_max3_f32 v240, v240, v111, v95
	v_max3_f32 v66, v66, v112, v96
	v_mfma_f32_32x32x16_bf16 v[146:161], v[76:79], v[178:181], v[146:161]
	v_max3_f32 v240, v240, v113, v97
	v_max3_f32 v240, v240, v66, v66
	v_mfma_f32_32x32x16_bf16 v[130:145], v[166:169], v[178:181], v[130:145]
	s_add_i32 s7, s7, 0x10000
	v_add_u32_e32 v0, s7, v227
	ds_read_b128 v[194:197], v0
	ds_read_b128 v[76:79], v0 offset:4096
	ds_read_b128 v[72:75], v0 offset:8192
	ds_read_b128 v[68:71], v0 offset:12288
	v_mov_b32_e32 v66, v240
	s_nop 1
	v_permlane32_swap_b32_e32 v240, v66
	v_max3_f32 v198, v240, v66, v66
	s_nop 0
	v_pk_add_f32 v[162:163], v[200:201], v[198:199]
	s_nop 0
	v_cmp_gt_f32_e32 vcc, v162, v163
	s_nop 1
	v_cndmask_b32_e32 v0, v201, v162, vcc
	v_cmp_gt_f32_e32 vcc, v0, v201
	s_cbranch_vccz .LBB0_226
	v_sub_f32_e32 v66, v201, v0
	v_exp_f32_e32 v66, v66
	v_xor_b32_e32 v162, 0x80000000, v0
	v_mov_b32_e32 v163, v162
	v_mov_b32_e32 v164, v162
	v_pk_mul_f32 v[64:65], v[64:65], v[66:67] op_sel_hi:[1,0]
	v_pk_mul_f32 v[62:63], v[62:63], v[66:67] op_sel_hi:[1,0]
	v_pk_mul_f32 v[60:61], v[60:61], v[66:67] op_sel_hi:[1,0]
	v_pk_mul_f32 v[58:59], v[58:59], v[66:67] op_sel_hi:[1,0]
	v_pk_mul_f32 v[56:57], v[56:57], v[66:67] op_sel_hi:[1,0]
	v_pk_mul_f32 v[54:55], v[54:55], v[66:67] op_sel_hi:[1,0]
	v_pk_mul_f32 v[52:53], v[52:53], v[66:67] op_sel_hi:[1,0]
	v_pk_mul_f32 v[50:51], v[50:51], v[66:67] op_sel_hi:[1,0]
	v_pk_mul_f32 v[48:49], v[48:49], v[66:67] op_sel_hi:[1,0]
	v_pk_mul_f32 v[46:47], v[46:47], v[66:67] op_sel_hi:[1,0]
	v_pk_mul_f32 v[44:45], v[44:45], v[66:67] op_sel_hi:[1,0]
	v_pk_mul_f32 v[42:43], v[42:43], v[66:67] op_sel_hi:[1,0]
	v_pk_mul_f32 v[40:41], v[40:41], v[66:67] op_sel_hi:[1,0]
	v_pk_mul_f32 v[38:39], v[38:39], v[66:67] op_sel_hi:[1,0]
	v_pk_mul_f32 v[36:37], v[36:37], v[66:67] op_sel_hi:[1,0]
	v_pk_mul_f32 v[34:35], v[34:35], v[66:67] op_sel_hi:[1,0]
	v_pk_mul_f32 v[32:33], v[32:33], v[66:67] op_sel_hi:[1,0]
	v_pk_mul_f32 v[30:31], v[30:31], v[66:67] op_sel_hi:[1,0]
	v_pk_mul_f32 v[28:29], v[28:29], v[66:67] op_sel_hi:[1,0]
	v_pk_mul_f32 v[26:27], v[26:27], v[66:67] op_sel_hi:[1,0]
	v_pk_mul_f32 v[24:25], v[24:25], v[66:67] op_sel_hi:[1,0]
	v_pk_mul_f32 v[22:23], v[22:23], v[66:67] op_sel_hi:[1,0]
	v_pk_mul_f32 v[20:21], v[20:21], v[66:67] op_sel_hi:[1,0]
	v_pk_mul_f32 v[18:19], v[18:19], v[66:67] op_sel_hi:[1,0]
	v_pk_mul_f32 v[16:17], v[16:17], v[66:67] op_sel_hi:[1,0]
	v_pk_mul_f32 v[14:15], v[14:15], v[66:67] op_sel_hi:[1,0]
	v_pk_mul_f32 v[12:13], v[12:13], v[66:67] op_sel_hi:[1,0]
	v_pk_mul_f32 v[10:11], v[10:11], v[66:67] op_sel_hi:[1,0]
	v_pk_mul_f32 v[8:9], v[8:9], v[66:67] op_sel_hi:[1,0]
	v_pk_mul_f32 v[6:7], v[6:7], v[66:67] op_sel_hi:[1,0]
	v_pk_mul_f32 v[4:5], v[4:5], v[66:67] op_sel_hi:[1,0]
	v_pk_mul_f32 v[2:3], v[2:3], v[66:67] op_sel_hi:[1,0]
	v_mul_f32_e32 v232, v232, v66
	v_mov_b32_e32 v165, v162
	v_mov_b32_e32 v166, v162
	v_mov_b32_e32 v167, v162
	v_mov_b32_e32 v168, v162
	v_mov_b32_e32 v169, v162
	v_mov_b32_e32 v170, v162
	v_mov_b32_e32 v171, v162
	v_mov_b32_e32 v172, v162
	v_mov_b32_e32 v173, v162
	v_mov_b32_e32 v174, v162
	v_mov_b32_e32 v175, v162
	v_mov_b32_e32 v176, v162
	v_mov_b32_e32 v177, v162
	v_mov_b32_e32 v201, v0
	v_mov_b32_e32 v66, v162
	v_mov_b32_e32 v115, v162
	v_mov_b32_e32 v116, v162
	v_mov_b32_e32 v117, v162
	v_mov_b32_e32 v118, v162
	v_mov_b32_e32 v119, v162
	v_mov_b32_e32 v120, v162
	v_mov_b32_e32 v121, v162
	v_mov_b32_e32 v122, v162
	v_mov_b32_e32 v123, v162
	v_mov_b32_e32 v124, v162
	v_mov_b32_e32 v125, v162
	v_mov_b32_e32 v126, v162
	v_mov_b32_e32 v127, v162
	v_mov_b32_e32 v128, v162
	v_mov_b32_e32 v129, v162
	v_sub_f32_e32 v0, v0, v200
	v_cmp_neq_f32_e32 vcc, 0, v0
	s_cbranch_vccz .LBB0_218

; #define DA_WAIT_BAR(N) do { asm volatile("s_waitcnt vmcnt(" #N ")" ::: "memory"); __builtin_amdgcn_s_barrier(); } while (0)
; __device__ __forceinline__ void dattn_unit(LAS unsigned char* lds, const bf16_t* Qp, const bf16_t* Kp, const bf16_t* Vtp, int qb, bf16_t* Op, const float* lq1, const float* lk1, const float* lq2, const float* lk2, const float* subg, float outscale, int tid) {
;     ...
;         DA_WAIT_BAR(4); if (kt + 4 < nk) DA_DMA(kt + 4, kt & 3); DA_QK(sa, mra, (kt + 2) & 3); DA_SOFTMAX_PV(sb, mrb, (kt + 1) & 3, false, kt + 1);
.LBB0_218:
	v_exp_f32_e32 v198, v98
	v_exp_f32_e32 v0, v99
	v_exp_f32_e32 v200, v100
	v_exp_f32_e32 v98, v101
	v_exp_f32_e32 v238, v102
	v_exp_f32_e32 v99, v103
	v_exp_f32_e32 v239, v104
	v_exp_f32_e32 v100, v105
	v_cvt_pk_bf16_f32 v240, v198, v0
	v_cvt_pk_bf16_f32 v241, v200, v98
	v_cvt_pk_bf16_f32 v242, v238, v99
	v_cvt_pk_bf16_f32 v243, v239, v100
	v_exp_f32_e32 v105, v106
	s_waitcnt lgkmcnt(0)
	v_mfma_f32_32x32x16_bf16 v[50:65], v[194:197], v[240:243], v[50:65]
	v_add_u32_e32 v248, s7, v219
	v_exp_f32_e32 v101, v107
	v_exp_f32_e32 v106, v108
	v_exp_f32_e32 v102, v109
	v_mfma_f32_32x32x16_bf16 v[34:49], v[76:79], v[240:243], v[34:49]
	s_add_i32 m0, s98, 0x2000
	v_lshl_add_u64 v[250:251], v[212:213], 0, s[36:37]
	global_load_lds_dwordx4 v[250:251], off
	v_exp_f32_e32 v107, v110
	v_exp_f32_e32 v103, v111
	v_exp_f32_e32 v108, v112
	v_mfma_f32_32x32x16_bf16 v[18:33], v[72:75], v[240:243], v[18:33]
	ds_read_b128 v[72:75], v248
	ds_read_b128 v[76:79], v248 offset:4096
	ds_read_b128 v[194:197], v248 offset:8192
	ds_read_b128 v[220:223], v248 offset:12288
	v_exp_f32_e32 v104, v113
	v_cvt_pk_bf16_f32 v244, v105, v101
	v_cvt_pk_bf16_f32 v245, v106, v102
	v_mfma_f32_32x32x16_bf16 v[2:17], v[68:71], v[240:243], v[2:17]
	v_cvt_pk_bf16_f32 v246, v107, v103
	v_cvt_pk_bf16_f32 v247, v108, v104
	v_exp_f32_e32 v109, v82
	v_exp_f32_e32 v82, v83
	s_waitcnt lgkmcnt(0)
	v_mfma_f32_32x32x16_bf16 v[50:65], v[72:75], v[244:247], v[50:65]
	v_add_u32_e32 v248, s7, v218
	v_exp_f32_e32 v110, v84
	v_exp_f32_e32 v83, v85
	v_exp_f32_e32 v111, v86
	v_mfma_f32_32x32x16_bf16 v[34:49], v[76:79], v[244:247], v[34:49]
	s_add_i32 m0, s99, 0x2000
	v_lshl_add_u64 v[250:251], v[214:215], 0, s[58:59]
	global_load_lds_dwordx4 v[250:251], off
	v_exp_f32_e32 v84, v87
	v_exp_f32_e32 v112, v88
	v_exp_f32_e32 v85, v89
	v_mfma_f32_32x32x16_bf16 v[18:33], v[194:197], v[244:247], v[18:33]
	ds_read_b128 v[68:71], v248
	ds_read_b128 v[72:75], v248 offset:4096
	ds_read_b128 v[76:79], v248 offset:8192
	ds_read_b128 v[194:197], v248 offset:12288
	v_exp_f32_e32 v90, v90
	v_exp_f32_e32 v86, v91
	v_exp_f32_e32 v91, v92
	v_mfma_f32_32x32x16_bf16 v[2:17], v[220:223], v[244:247], v[2:17]
	v_exp_f32_e32 v87, v93
	v_exp_f32_e32 v92, v94
	v_exp_f32_e32 v88, v95
	v_exp_f32_e32 v93, v96
	v_exp_f32_e32 v89, v97
	v_cvt_pk_bf16_f32 v94, v109, v82
	v_cvt_pk_bf16_f32 v95, v110, v83
	v_cvt_pk_bf16_f32 v96, v111, v84
	v_cvt_pk_bf16_f32 v97, v112, v85
	v_add_f32_e32 v240, 0, v198
	v_add_f32_e32 v241, 0, v0
	s_waitcnt lgkmcnt(0)
	v_mfma_f32_32x32x16_bf16 v[50:65], v[68:71], v[94:97], v[50:65]
	v_add_u32_e32 v113, s7, v217
	v_cvt_pk_bf16_f32 v248, v90, v86
	v_cvt_pk_bf16_f32 v249, v91, v87
	v_add_f32_e32 v240, v200, v240
	v_add_f32_e32 v241, v98, v241
	v_add_f32_e32 v240, v238, v240
	v_mfma_f32_32x32x16_bf16 v[34:49], v[72:75], v[94:97], v[34:49]
	v_cvt_pk_bf16_f32 v250, v92, v88
	v_cvt_pk_bf16_f32 v251, v93, v89
	v_add_f32_e32 v241, v99, v241
	v_add_f32_e32 v240, v239, v240
	v_add_f32_e32 v241, v100, v241
	v_mfma_f32_32x32x16_bf16 v[18:33], v[76:79], v[94:97], v[18:33]
	ds_read_b128 v[68:71], v113
	ds_read_b128 v[72:75], v113 offset:4096
	ds_read_b128 v[76:79], v113 offset:8192
	ds_read_b128 v[220:223], v113 offset:12288
	v_add_f32_e32 v240, v105, v240
	v_add_f32_e32 v241, v101, v241
	v_add_f32_e32 v240, v106, v240
	v_add_f32_e32 v241, v102, v241
	v_mfma_f32_32x32x16_bf16 v[2:17], v[194:197], v[94:97], v[2:17]
	v_add_f32_e32 v240, v107, v240
	v_add_f32_e32 v241, v103, v241
	v_add_f32_e32 v240, v108, v240
	v_add_f32_e32 v241, v104, v241
	v_add_f32_e32 v240, v109, v240
	v_add_f32_e32 v241, v82, v241
	s_waitcnt lgkmcnt(0)
	v_mfma_f32_32x32x16_bf16 v[50:65], v[68:71], v[248:251], v[50:65]
	v_add_f32_e32 v240, v110, v240
	v_add_f32_e32 v241, v83, v241
	v_add_f32_e32 v240, v111, v240
	v_add_f32_e32 v241, v84, v241
	v_add_f32_e32 v240, v112, v240
	v_add_f32_e32 v241, v85, v241
	v_mfma_f32_32x32x16_bf16 v[34:49], v[72:75], v[248:251], v[34:49]
	v_add_f32_e32 v240, v90, v240
	v_add_f32_e32 v241, v86, v241
	v_add_f32_e32 v240, v91, v240
	v_add_f32_e32 v241, v87, v241
	v_add_f32_e32 v240, v92, v240
	v_add_f32_e32 v241, v88, v241
	v_mfma_f32_32x32x16_bf16 v[18:33], v[76:79], v[248:251], v[18:33]
	v_add_f32_e32 v240, v93, v240
	v_add_f32_e32 v241, v89, v241
	v_add_f32_e32 v0, v241, v240
	v_add_f32_e32 v0, v232, v0
	v_mfma_f32_32x32x16_bf16 v[2:17], v[220:223], v[248:251], v[2:17]
	s_waitcnt vmcnt(4)
	s_add_i32 s17, s4, 4
	s_cmp_gt_u32 s17, s11
	s_barrier
	s_cbranch_scc1 .LBB0_220
	s_add_i32 s17, s15, s6
	s_add_i32 s7, s7, s14
	v_lshl_add_u64 v[68:69], v[208:209], 0, s[22:23]
	s_mov_b32 m0, s17
	s_mov_b64 s[34:35], 0x20400200
	global_load_lds_dwordx4 v[68:69], off
	v_lshl_add_u64 v[68:69], v[210:211], 0, s[34:35]
	s_mov_b32 m0, s7
	s_nop 0
	global_load_lds_dwordx4 v[68:69], off
	v_lshl_add_u64 v[68:69], v[212:213], 0, s[22:23]
	s_add_i32 m0, s17, 0x2000
	s_nop 0
	global_load_lds_dwordx4 v[68:69], off
	v_lshl_add_u64 v[68:69], v[214:215], 0, s[34:35]
	s_add_i32 m0, s7, 0x2000
	s_nop 0
	global_load_lds_dwordx4 v[68:69], off

; __device__ __forceinline__ unsigned cvt_pk_bf16(float lo, float hi) { const f32x2_t v = {lo, hi}; const bf16x2_t b = __builtin_convertvector(v, bf16x2_t); return __builtin_bit_cast(unsigned, b); }
; template <int N> __device__ __forceinline__ float dpp_ror(float v) { return __builtin_bit_cast(float, __builtin_amdgcn_update_dpp(0, __builtin_bit_cast(int, v), 0x120 + N, 0xf, 0xf, false)); }
;     __device__ __forceinline__ void operator()(const Acc& acc, const Unit& u, int wr, int wc, int fr, int fq) const {
;     ...
;                 for (int m = 0; m < 4; ++m) {
;                     const int rt = ai * 128 + wr * 64 + m * 16 + fr;
;                     const f32x4 g = acc[ai][0][m][n], up = acc[ai][1][m][n];
;                     const f32x4 gp = (m == 0) ? hg : acc[ai][0][m == 0 ? 0 : m - 1][n], upp = (m == 0) ? hu : acc[ai][1][m == 0 ? 0 : m - 1][n];
;                     f32x4 g1, g2, u1, u2;
; #pragma unroll
;                     for (int j = 0; j < 4; ++j) {
;                         g1[j] = dpp_ror<1>((fr == 15) ? gp[j] : g[j]); g2[j] = dpp_ror<2>((fr >= 14) ? gp[j] : g[j]);
;                         u1[j] = dpp_ror<1>((fr == 15) ? upp[j] : up[j]); u2[j] = dpp_ror<2>((fr >= 14) ? upp[j] : up[j]);
;                     }
;                     const f32x4 hcg = gb + gw0 * g2 + gw1 * g1 + gw2 * g, hcu = ub + uw0 * u2 + uw1 * u1 + uw2 * up;
;                     f32x4 a;
; #pragma unroll
;                     for (int j = 0; j < 4; ++j) a[j] = hcg[j] * __builtin_amdgcn_rcpf(1.f + __builtin_amdgcn_exp2f(-1.4426950408889634f * hcg[j])) * hcu[j];
;                     if (rt >= 2) { u32x2 w; w.x = cvt_pk_bf16(a[0], a[1]); w.y = cvt_pk_bf16(a[2], a[3]); *(u32x2*)(act + ((size_t)u.pm * 256 + rt) * DFF + ch) = w; }
.LBB0_692:
	s_or_b64 exec, exec, s[18:19]
	s_waitcnt lgkmcnt(1)
	v_cndmask_b32_e64 v0, v158, v162, s[42:43]
	v_cndmask_b32_e64 v244, v158, v162, s[40:41]
	s_waitcnt lgkmcnt(0)
	v_mov_b32_dpp v216, v0 row_ror:1 row_mask:0xf bank_mask:0xf
	v_mov_b32_dpp v218, v244 row_ror:2 row_mask:0xf bank_mask:0xf
	v_cndmask_b32_e64 v245, v154, v166, s[42:43]
	v_cndmask_b32_e64 v0, v154, v166, s[40:41]
	v_cndmask_b32_e64 v244, v159, v163, s[42:43]
	v_mov_b32_dpp v210, v245 row_ror:1 row_mask:0xf bank_mask:0xf
	v_mov_b32_dpp v214, v0 row_ror:2 row_mask:0xf bank_mask:0xf
	v_mov_b32_dpp v217, v244 row_ror:1 row_mask:0xf bank_mask:0xf
	v_cndmask_b32_e64 v245, v159, v163, s[40:41]
	v_cndmask_b32_e64 v0, v155, v167, s[42:43]
	s_ashr_i32 s17, s16, 31
	v_mov_b32_dpp v219, v245 row_ror:2 row_mask:0xf bank_mask:0xf
	s_lshl_b64 s[16:17], s[16:17], 8
	v_mov_b32_dpp v211, v0 row_ror:1 row_mask:0xf bank_mask:0xf
	v_cndmask_b32_e64 v244, v155, v167, s[40:41]
	v_lshl_add_u64 v[162:163], s[16:17], 0, v[178:179]
	v_cndmask_b32_e64 v245, v160, v164, s[42:43]
	v_mov_b32_dpp v215, v244 row_ror:2 row_mask:0xf bank_mask:0xf
	v_cndmask_b32_e64 v0, v160, v164, s[40:41]
	v_mov_b32_dpp v208, v245 row_ror:1 row_mask:0xf bank_mask:0xf
	v_cndmask_b32_e64 v244, v156, v168, s[42:43]
	v_mov_b32_dpp v212, v0 row_ror:2 row_mask:0xf bank_mask:0xf
	v_cndmask_b32_e64 v245, v156, v168, s[40:41]
	v_mov_b32_dpp v164, v244 row_ror:1 row_mask:0xf bank_mask:0xf
	v_cndmask_b32_e64 v0, v161, v165, s[42:43]
	v_mov_b32_dpp v166, v245 row_ror:2 row_mask:0xf bank_mask:0xf
	v_cndmask_b32_e64 v244, v161, v165, s[40:41]
	v_mov_b32_dpp v209, v0 row_ror:1 row_mask:0xf bank_mask:0xf
	v_cndmask_b32_e64 v245, v157, v169, s[42:43]
	v_mov_b32_dpp v213, v244 row_ror:2 row_mask:0xf bank_mask:0xf
	v_cndmask_b32_e64 v0, v157, v169, s[40:41]
	v_mov_b32_dpp v165, v245 row_ror:1 row_mask:0xf bank_mask:0xf
	s_nop 0
	v_mov_b32_dpp v167, v0 row_ror:2 row_mask:0xf bank_mask:0xf
	s_and_saveexec_b64 s[18:19], s[44:45]
	s_cbranch_execz .LBB0_694
	s_waitcnt vmcnt(4)
	v_pk_fma_f32 v[168:169], v[130:131], v[218:219], v[142:143]
	v_pk_fma_f32 v[212:213], v[132:133], v[212:213], v[144:145]
	v_pk_fma_f32 v[168:169], v[134:135], v[216:217], v[168:169]
	v_pk_fma_f32 v[208:209], v[136:137], v[208:209], v[212:213]
	v_pk_fma_f32 v[168:169], v[158:159], v[138:139], v[168:169]
	v_pk_fma_f32 v[208:209], v[160:161], v[140:141], v[208:209]
	v_mul_f32_e32 v0, 0xbfb8aa3b, v168
	v_exp_f32_e32 v0, v0
	v_mul_f32_e32 v216, 0xbfb8aa3b, v169
	v_exp_f32_e32 v216, v216
	v_mul_f32_e32 v212, 0xbfb8aa3b, v209
	v_add_f32_e32 v0, 1.0, v0
	v_exp_f32_e32 v212, v212
	v_add_f32_e32 v217, 1.0, v216
	v_rcp_f32_e32 v216, v0
	v_mul_f32_e32 v0, 0xbfb8aa3b, v208
	v_rcp_f32_e32 v217, v217
	v_exp_f32_e32 v0, v0
	s_waitcnt vmcnt(0)
	v_pk_fma_f32 v[214:215], v[114:115], v[214:215], v[126:127]
	v_pk_fma_f32 v[166:167], v[116:117], v[166:167], v[128:129]
	v_pk_fma_f32 v[210:211], v[118:119], v[210:211], v[214:215]
	v_pk_mul_f32 v[168:169], v[168:169], v[216:217]
	v_pk_fma_f32 v[210:211], v[154:155], v[122:123], v[210:211]
	v_add_f32_e32 v0, 1.0, v0
	v_pk_mul_f32 v[168:169], v[210:211], v[168:169]
	v_rcp_f32_e32 v210, v0
	v_add_f32_e32 v0, 1.0, v212
	v_rcp_f32_e32 v211, v0
	v_pk_fma_f32 v[164:165], v[120:121], v[164:165], v[166:167]
	v_pk_mul_f32 v[166:167], v[208:209], v[210:211]
	v_pk_fma_f32 v[164:165], v[156:157], v[124:125], v[164:165]
	s_nop 0
	v_pk_mul_f32 v[164:165], v[164:165], v[166:167]
	v_cvt_pk_bf16_f32 v166, v168, v169
	v_cvt_pk_bf16_f32 v167, v164, v165
	v_mov_b64_e32 v[164:165], s[12:13]
	v_mad_u64_u32 v[164:165], s[26:27], v162, s60, v[164:165]
	v_mad_i32_i24 v165, v163, s60, v165
	v_lshl_add_u64 v[164:165], v[202:203], 1, v[164:165]
	global_store_dwordx2 v[164:165], v[166:167], off
.LBB0_694:
	s_or_b64 exec, exec, s[18:19]
	v_cndmask_b32_e64 v0, v150, v158, s[42:43]
	v_cndmask_b32_e64 v244, v150, v158, s[40:41]
	v_cndmask_b32_e64 v245, v146, v154, s[42:43]
	v_mov_b32_dpp v208, v0 row_ror:1 row_mask:0xf bank_mask:0xf
	v_mov_b32_dpp v210, v244 row_ror:2 row_mask:0xf bank_mask:0xf
	v_mov_b32_dpp v166, v245 row_ror:1 row_mask:0xf bank_mask:0xf
	v_cndmask_b32_e64 v0, v146, v154, s[40:41]
	v_cndmask_b32_e64 v244, v151, v159, s[42:43]
	v_cndmask_b32_e64 v245, v151, v159, s[40:41]
	v_mov_b32_dpp v168, v0 row_ror:2 row_mask:0xf bank_mask:0xf
	v_mov_b32_dpp v209, v244 row_ror:1 row_mask:0xf bank_mask:0xf
	s_andn2_b64 vcc, exec, s[20:21]
	v_mov_b32_dpp v211, v245 row_ror:2 row_mask:0xf bank_mask:0xf
	v_cndmask_b32_e64 v0, v147, v155, s[42:43]
	v_cndmask_b32_e64 v244, v147, v155, s[40:41]
	v_lshl_add_u64 v[154:155], s[16:17], 0, v[182:183]
	v_mov_b32_dpp v167, v0 row_ror:1 row_mask:0xf bank_mask:0xf
	v_mov_b32_dpp v169, v244 row_ror:2 row_mask:0xf bank_mask:0xf
	v_cndmask_b32_e64 v245, v152, v160, s[42:43]
	v_cndmask_b32_e64 v0, v152, v160, s[40:41]
	v_cndmask_b32_e64 v244, v148, v156, s[42:43]
	v_mov_b32_dpp v164, v245 row_ror:1 row_mask:0xf bank_mask:0xf
	v_mov_b32_dpp v160, v0 row_ror:2 row_mask:0xf bank_mask:0xf
	v_mov_b32_dpp v158, v244 row_ror:1 row_mask:0xf bank_mask:0xf
	v_cndmask_b32_e64 v245, v148, v156, s[40:41]
	v_cndmask_b32_e64 v0, v153, v161, s[42:43]
	v_cndmask_b32_e64 v244, v153, v161, s[40:41]
	v_mov_b32_dpp v156, v245 row_ror:2 row_mask:0xf bank_mask:0xf
	v_mov_b32_dpp v165, v0 row_ror:1 row_mask:0xf bank_mask:0xf
	v_mov_b32_dpp v161, v244 row_ror:2 row_mask:0xf bank_mask:0xf
	v_cndmask_b32_e64 v245, v149, v157, s[42:43]
	v_cndmask_b32_e64 v0, v149, v157, s[40:41]
	s_nop 0
	v_mov_b32_dpp v159, v245 row_ror:1 row_mask:0xf bank_mask:0xf
	v_mov_b32_dpp v157, v0 row_ror:2 row_mask:0xf bank_mask:0xf
	v_cndmask_b32_e64 v0, 0, 1, s[20:21]
	v_cmp_ne_u32_e64 s[56:57], 1, v0
	s_cbranch_vccnz .LBB0_696
; __device__ __forceinline__ unsigned cvt_pk_bf16(float lo, float hi) { const f32x2_t v = {lo, hi}; const bf16x2_t b = __builtin_convertvector(v, bf16x2_t); return __builtin_bit_cast(unsigned, b); }
; template <int N> __device__ __forceinline__ float dpp_ror(float v) { return __builtin_bit_cast(float, __builtin_amdgcn_update_dpp(0, __builtin_bit_cast(int, v), 0x120 + N, 0xf, 0xf, false)); }
;     __device__ __forceinline__ void operator()(const Acc& acc, const Unit& u, int wr, int wc, int fr, int fq) const {
;     ...
;                 for (int m = 0; m < 4; ++m) {
;                     const int rt = ai * 128 + wr * 64 + m * 16 + fr;
;                     const f32x4 g = acc[ai][0][m][n], up = acc[ai][1][m][n];
;                     const f32x4 gp = (m == 0) ? hg : acc[ai][0][m == 0 ? 0 : m - 1][n], upp = (m == 0) ? hu : acc[ai][1][m == 0 ? 0 : m - 1][n];
;                     f32x4 g1, g2, u1, u2;
; #pragma unroll
;                     for (int j = 0; j < 4; ++j) {
;                         g1[j] = dpp_ror<1>((fr == 15) ? gp[j] : g[j]); g2[j] = dpp_ror<2>((fr >= 14) ? gp[j] : g[j]);
;                         u1[j] = dpp_ror<1>((fr == 15) ? upp[j] : up[j]); u2[j] = dpp_ror<2>((fr >= 14) ? upp[j] : up[j]);
;                     }
;                     const f32x4 hcg = gb + gw0 * g2 + gw1 * g1 + gw2 * g, hcu = ub + uw0 * u2 + uw1 * u1 + uw2 * up;
;                     f32x4 a;
; #pragma unroll
;                     for (int j = 0; j < 4; ++j) a[j] = hcg[j] * __builtin_amdgcn_rcpf(1.f + __builtin_amdgcn_exp2f(-1.4426950408889634f * hcg[j])) * hcu[j];
;                     if (rt >= 2) { u32x2 w; w.x = cvt_pk_bf16(a[0], a[1]); w.y = cvt_pk_bf16(a[2], a[3]); *(u32x2*)(act + ((size_t)u.pm * 256 + rt) * DFF + ch) = w; }
	s_waitcnt vmcnt(4)
	v_pk_fma_f32 v[210:211], v[130:131], v[210:211], v[142:143]
	v_pk_fma_f32 v[160:161], v[132:133], v[160:161], v[144:145]
	v_pk_fma_f32 v[208:209], v[134:135], v[208:209], v[210:211]
	v_pk_fma_f32 v[160:161], v[136:137], v[164:165], v[160:161]
	v_pk_fma_f32 v[208:209], v[150:151], v[138:139], v[208:209]
	v_pk_fma_f32 v[160:161], v[152:153], v[140:141], v[160:161]
	v_mul_f32_e32 v0, 0xbfb8aa3b, v208
	v_mul_f32_e32 v210, 0xbfb8aa3b, v209
	v_exp_f32_e32 v0, v0
	v_exp_f32_e32 v210, v210
	s_waitcnt vmcnt(0)
	v_pk_fma_f32 v[168:169], v[114:115], v[168:169], v[126:127]
	v_mul_f32_e32 v164, 0xbfb8aa3b, v161
	v_add_f32_e32 v0, 1.0, v0
	v_add_f32_e32 v211, 1.0, v210
	v_rcp_f32_e32 v210, v0
	v_rcp_f32_e32 v211, v211
	v_mul_f32_e32 v0, 0xbfb8aa3b, v160
	v_exp_f32_e32 v0, v0
	v_pk_fma_f32 v[166:167], v[118:119], v[166:167], v[168:169]
	v_pk_mul_f32 v[168:169], v[208:209], v[210:211]
	v_exp_f32_e32 v208, v164
	v_pk_fma_f32 v[166:167], v[146:147], v[122:123], v[166:167]
	v_add_f32_e32 v0, 1.0, v0
	v_pk_mul_f32 v[164:165], v[166:167], v[168:169]
	v_rcp_f32_e32 v166, v0
	v_add_f32_e32 v0, 1.0, v208
	v_rcp_f32_e32 v167, v0
	v_pk_fma_f32 v[156:157], v[116:117], v[156:157], v[128:129]
	s_nop 0
	v_pk_fma_f32 v[156:157], v[120:121], v[158:159], v[156:157]
	v_pk_mul_f32 v[158:159], v[160:161], v[166:167]
	v_pk_fma_f32 v[156:157], v[148:149], v[124:125], v[156:157]
	s_nop 0
	v_pk_mul_f32 v[156:157], v[156:157], v[158:159]
	v_cvt_pk_bf16_f32 v158, v164, v165
	v_cvt_pk_bf16_f32 v159, v156, v157
	v_mov_b64_e32 v[156:157], s[12:13]
	v_mad_u64_u32 v[156:157], s[18:19], v154, s60, v[156:157]
	v_mad_i32_i24 v157, v155, s60, v157
	v_lshl_add_u64 v[156:157], v[202:203], 1, v[156:157]
	global_store_dwordx2 v[156:157], v[158:159], off
.LBB0_696:
	v_cndmask_b32_e64 v0, v110, v150, s[42:43]
	v_cndmask_b32_e64 v244, v110, v150, s[40:41]
	v_cndmask_b32_e64 v245, v106, v146, s[42:43]
	v_mov_b32_dpp v164, v0 row_ror:1 row_mask:0xf bank_mask:0xf
	v_mov_b32_dpp v166, v244 row_ror:2 row_mask:0xf bank_mask:0xf
	v_mov_b32_dpp v158, v245 row_ror:1 row_mask:0xf bank_mask:0xf
	v_cndmask_b32_e64 v0, v106, v146, s[40:41]
	v_cndmask_b32_e64 v244, v111, v151, s[42:43]
	v_cndmask_b32_e64 v245, v111, v151, s[40:41]
	v_mov_b32_dpp v160, v0 row_ror:2 row_mask:0xf bank_mask:0xf
	v_mov_b32_dpp v165, v244 row_ror:1 row_mask:0xf bank_mask:0xf
	s_and_b64 vcc, exec, s[56:57]
	v_mov_b32_dpp v167, v245 row_ror:2 row_mask:0xf bank_mask:0xf
	v_cndmask_b32_e64 v0, v107, v147, s[42:43]
	v_cndmask_b32_e64 v244, v107, v147, s[40:41]
	v_lshl_add_u64 v[146:147], s[16:17], 0, v[184:185]
	v_mov_b32_dpp v159, v0 row_ror:1 row_mask:0xf bank_mask:0xf
	v_mov_b32_dpp v161, v244 row_ror:2 row_mask:0xf bank_mask:0xf
	v_cndmask_b32_e64 v245, v112, v152, s[42:43]
	v_cndmask_b32_e64 v0, v112, v152, s[40:41]
	v_cndmask_b32_e64 v244, v108, v148, s[42:43]
	v_mov_b32_dpp v156, v245 row_ror:1 row_mask:0xf bank_mask:0xf
	v_mov_b32_dpp v152, v0 row_ror:2 row_mask:0xf bank_mask:0xf
	v_mov_b32_dpp v150, v244 row_ror:1 row_mask:0xf bank_mask:0xf
	v_cndmask_b32_e64 v245, v108, v148, s[40:41]
	v_cndmask_b32_e64 v0, v113, v153, s[42:43]
	v_cndmask_b32_e64 v244, v113, v153, s[40:41]
	v_mov_b32_dpp v148, v245 row_ror:2 row_mask:0xf bank_mask:0xf
	v_mov_b32_dpp v157, v0 row_ror:1 row_mask:0xf bank_mask:0xf
	v_mov_b32_dpp v153, v244 row_ror:2 row_mask:0xf bank_mask:0xf
	v_cndmask_b32_e64 v245, v109, v149, s[42:43]
	v_cndmask_b32_e64 v0, v109, v149, s[40:41]
	s_nop 0
	v_mov_b32_dpp v151, v245 row_ror:1 row_mask:0xf bank_mask:0xf
	v_mov_b32_dpp v149, v0 row_ror:2 row_mask:0xf bank_mask:0xf
	s_cbranch_vccnz .LBB0_698
	s_waitcnt vmcnt(4)
	v_pk_fma_f32 v[166:167], v[130:131], v[166:167], v[142:143]
	v_pk_fma_f32 v[152:153], v[132:133], v[152:153], v[144:145]
	v_pk_fma_f32 v[164:165], v[134:135], v[164:165], v[166:167]
	v_pk_fma_f32 v[152:153], v[136:137], v[156:157], v[152:153]
	v_pk_fma_f32 v[164:165], v[110:111], v[138:139], v[164:165]
	v_pk_fma_f32 v[152:153], v[112:113], v[140:141], v[152:153]
	v_mul_f32_e32 v0, 0xbfb8aa3b, v164
	v_mul_f32_e32 v166, 0xbfb8aa3b, v165
	v_exp_f32_e32 v0, v0
	v_exp_f32_e32 v166, v166
	s_waitcnt vmcnt(0)
	v_pk_fma_f32 v[160:161], v[114:115], v[160:161], v[126:127]
	v_mul_f32_e32 v156, 0xbfb8aa3b, v153
	v_add_f32_e32 v0, 1.0, v0
	v_add_f32_e32 v167, 1.0, v166
	v_rcp_f32_e32 v166, v0
	v_rcp_f32_e32 v167, v167
	v_mul_f32_e32 v0, 0xbfb8aa3b, v152
	v_exp_f32_e32 v0, v0
	v_pk_fma_f32 v[158:159], v[118:119], v[158:159], v[160:161]
	v_pk_mul_f32 v[160:161], v[164:165], v[166:167]
	v_exp_f32_e32 v164, v156
	v_pk_fma_f32 v[158:159], v[106:107], v[122:123], v[158:159]
	v_add_f32_e32 v0, 1.0, v0
	v_pk_mul_f32 v[156:157], v[158:159], v[160:161]
	v_rcp_f32_e32 v158, v0
	v_add_f32_e32 v0, 1.0, v164
	v_rcp_f32_e32 v159, v0
	v_pk_fma_f32 v[148:149], v[116:117], v[148:149], v[128:129]
	s_nop 0
	v_pk_fma_f32 v[148:149], v[120:121], v[150:151], v[148:149]
	v_pk_mul_f32 v[150:151], v[152:153], v[158:159]
	v_pk_fma_f32 v[148:149], v[108:109], v[124:125], v[148:149]
	s_nop 0
	v_pk_mul_f32 v[148:149], v[148:149], v[150:151]
	v_cvt_pk_bf16_f32 v150, v156, v157
	v_cvt_pk_bf16_f32 v151, v148, v149
	v_mov_b64_e32 v[148:149], s[12:13]
	v_mad_u64_u32 v[148:149], s[18:19], v146, s60, v[148:149]
	v_mad_i32_i24 v149, v147, s60, v149
	v_lshl_add_u64 v[148:149], v[202:203], 1, v[148:149]
	global_store_dwordx2 v[148:149], v[150:151], off
; __device__ __forceinline__ unsigned cvt_pk_bf16(float lo, float hi) { const f32x2_t v = {lo, hi}; const bf16x2_t b = __builtin_convertvector(v, bf16x2_t); return __builtin_bit_cast(unsigned, b); }
; template <int N> __device__ __forceinline__ float dpp_ror(float v) { return __builtin_bit_cast(float, __builtin_amdgcn_update_dpp(0, __builtin_bit_cast(int, v), 0x120 + N, 0xf, 0xf, false)); }
;     __device__ __forceinline__ void operator()(const Acc& acc, const Unit& u, int wr, int wc, int fr, int fq) const {
;     ...
;                 for (int m = 0; m < 4; ++m) {
;                     const int rt = ai * 128 + wr * 64 + m * 16 + fr;
;                     const f32x4 g = acc[ai][0][m][n], up = acc[ai][1][m][n];
;                     const f32x4 gp = (m == 0) ? hg : acc[ai][0][m == 0 ? 0 : m - 1][n], upp = (m == 0) ? hu : acc[ai][1][m == 0 ? 0 : m - 1][n];
;                     f32x4 g1, g2, u1, u2;
; #pragma unroll
;                     for (int j = 0; j < 4; ++j) {
;                         g1[j] = dpp_ror<1>((fr == 15) ? gp[j] : g[j]); g2[j] = dpp_ror<2>((fr >= 14) ? gp[j] : g[j]);
;                         u1[j] = dpp_ror<1>((fr == 15) ? upp[j] : up[j]); u2[j] = dpp_ror<2>((fr >= 14) ? upp[j] : up[j]);
;                     }
;                     const f32x4 hcg = gb + gw0 * g2 + gw1 * g1 + gw2 * g, hcu = ub + uw0 * u2 + uw1 * u1 + uw2 * up;
;                     f32x4 a;
; #pragma unroll
;                     for (int j = 0; j < 4; ++j) a[j] = hcg[j] * __builtin_amdgcn_rcpf(1.f + __builtin_amdgcn_exp2f(-1.4426950408889634f * hcg[j])) * hcu[j];
;                     if (rt >= 2) { u32x2 w; w.x = cvt_pk_bf16(a[0], a[1]); w.y = cvt_pk_bf16(a[2], a[3]); *(u32x2*)(act + ((size_t)u.pm * 256 + rt) * DFF + ch) = w; }
.LBB0_698:
	v_cndmask_b32_e64 v0, v102, v110, s[42:43]
	v_cndmask_b32_e64 v244, v102, v110, s[40:41]
	v_cndmask_b32_e64 v245, v98, v106, s[42:43]
	v_mov_b32_dpp v156, v0 row_ror:1 row_mask:0xf bank_mask:0xf
	v_mov_b32_dpp v158, v244 row_ror:2 row_mask:0xf bank_mask:0xf
	v_mov_b32_dpp v148, v245 row_ror:1 row_mask:0xf bank_mask:0xf
	v_cndmask_b32_e64 v0, v98, v106, s[40:41]
	v_cndmask_b32_e64 v244, v103, v111, s[42:43]
	v_cndmask_b32_e64 v245, v103, v111, s[40:41]
	v_mov_b32_dpp v152, v0 row_ror:2 row_mask:0xf bank_mask:0xf
	v_mov_b32_dpp v157, v244 row_ror:1 row_mask:0xf bank_mask:0xf
	v_mov_b32_dpp v159, v245 row_ror:2 row_mask:0xf bank_mask:0xf
	v_cndmask_b32_e64 v0, v99, v107, s[42:43]
	s_and_b64 vcc, exec, s[56:57]
	v_cndmask_b32_e64 v244, v99, v107, s[40:41]
	v_mov_b32_dpp v149, v0 row_ror:1 row_mask:0xf bank_mask:0xf
	v_cndmask_b32_e64 v245, v104, v112, s[42:43]
	v_mov_b32_dpp v153, v244 row_ror:2 row_mask:0xf bank_mask:0xf
	v_cndmask_b32_e64 v0, v104, v112, s[40:41]
	v_mov_b32_dpp v110, v245 row_ror:1 row_mask:0xf bank_mask:0xf
	v_cndmask_b32_e64 v244, v100, v108, s[42:43]
	v_mov_b32_dpp v150, v0 row_ror:2 row_mask:0xf bank_mask:0xf
	v_cndmask_b32_e64 v245, v100, v108, s[40:41]
	v_mov_b32_dpp v106, v244 row_ror:1 row_mask:0xf bank_mask:0xf
	v_cndmask_b32_e64 v0, v105, v113, s[42:43]
	v_mov_b32_dpp v108, v245 row_ror:2 row_mask:0xf bank_mask:0xf
	v_cndmask_b32_e64 v244, v105, v113, s[40:41]
	v_mov_b32_dpp v111, v0 row_ror:1 row_mask:0xf bank_mask:0xf
	v_lshl_add_u64 v[112:113], s[16:17], 0, v[186:187]
	v_mov_b32_dpp v151, v244 row_ror:2 row_mask:0xf bank_mask:0xf
	v_cndmask_b32_e64 v245, v101, v109, s[42:43]
	v_cndmask_b32_e64 v0, v101, v109, s[40:41]
	s_nop 0
	v_mov_b32_dpp v107, v245 row_ror:1 row_mask:0xf bank_mask:0xf
	v_mov_b32_dpp v109, v0 row_ror:2 row_mask:0xf bank_mask:0xf
	s_cbranch_vccnz .LBB0_700
	s_waitcnt vmcnt(4)
	v_pk_fma_f32 v[158:159], v[130:131], v[158:159], v[142:143]
	s_waitcnt vmcnt(0)
	v_pk_fma_f32 v[152:153], v[114:115], v[152:153], v[126:127]
	v_pk_fma_f32 v[156:157], v[134:135], v[156:157], v[158:159]
	v_pk_fma_f32 v[148:149], v[118:119], v[148:149], v[152:153]
	v_pk_fma_f32 v[102:103], v[102:103], v[138:139], v[156:157]
	v_pk_fma_f32 v[98:99], v[98:99], v[122:123], v[148:149]
	v_mul_f32_e32 v0, 0xbfb8aa3b, v102
	v_exp_f32_e32 v0, v0
	v_mul_f32_e32 v156, 0xbfb8aa3b, v103
	v_exp_f32_e32 v156, v156
	v_pk_fma_f32 v[148:149], v[132:133], v[150:151], v[144:145]
	v_add_f32_e32 v0, 1.0, v0
	v_pk_fma_f32 v[110:111], v[136:137], v[110:111], v[148:149]
	v_add_f32_e32 v157, 1.0, v156
	v_pk_fma_f32 v[104:105], v[104:105], v[140:141], v[110:111]
	v_rcp_f32_e32 v156, v0
	v_mul_f32_e32 v0, 0xbfb8aa3b, v104
	v_rcp_f32_e32 v157, v157
	v_exp_f32_e32 v0, v0
	v_mul_f32_e32 v110, 0xbfb8aa3b, v105
	v_exp_f32_e32 v110, v110
	v_pk_mul_f32 v[102:103], v[102:103], v[156:157]
	v_add_f32_e32 v0, 1.0, v0
	v_pk_mul_f32 v[98:99], v[98:99], v[102:103]
	v_rcp_f32_e32 v102, v0
	v_add_f32_e32 v0, 1.0, v110
	v_rcp_f32_e32 v103, v0
	v_pk_fma_f32 v[108:109], v[116:117], v[108:109], v[128:129]
	v_cvt_pk_bf16_f32 v98, v98, v99
	v_pk_fma_f32 v[106:107], v[120:121], v[106:107], v[108:109]
	v_pk_mul_f32 v[102:103], v[104:105], v[102:103]
	v_pk_fma_f32 v[100:101], v[100:101], v[124:125], v[106:107]
	s_nop 0
	v_pk_mul_f32 v[100:101], v[100:101], v[102:103]
	s_nop 0
	v_cvt_pk_bf16_f32 v99, v100, v101
	v_mov_b64_e32 v[100:101], s[12:13]
	v_mad_u64_u32 v[100:101], s[18:19], v112, s60, v[100:101]
	v_mad_i32_i24 v101, v113, s60, v101
	v_lshl_add_u64 v[100:101], v[202:203], 1, v[100:101]
	global_store_dwordx2 v[100:101], v[98:99], off

; __device__ __forceinline__ unsigned cvt_pk_bf16(float lo, float hi) { const f32x2_t v = {lo, hi}; const bf16x2_t b = __builtin_convertvector(v, bf16x2_t); return __builtin_bit_cast(unsigned, b); }
; template <int N> __device__ __forceinline__ float dpp_ror(float v) { return __builtin_bit_cast(float, __builtin_amdgcn_update_dpp(0, __builtin_bit_cast(int, v), 0x120 + N, 0xf, 0xf, false)); }
;     __device__ __forceinline__ void operator()(const Acc& acc, const Unit& u, int wr, int wc, int fr, int fq) const {
;     ...
;                 for (int m = 0; m < 4; ++m) {
;                     const int rt = ai * 128 + wr * 64 + m * 16 + fr;
;                     const f32x4 g = acc[ai][0][m][n], up = acc[ai][1][m][n];
;                     const f32x4 gp = (m == 0) ? hg : acc[ai][0][m == 0 ? 0 : m - 1][n], upp = (m == 0) ? hu : acc[ai][1][m == 0 ? 0 : m - 1][n];
;                     f32x4 g1, g2, u1, u2;
; #pragma unroll
;                     for (int j = 0; j < 4; ++j) {
;                         g1[j] = dpp_ror<1>((fr == 15) ? gp[j] : g[j]); g2[j] = dpp_ror<2>((fr >= 14) ? gp[j] : g[j]);
;                         u1[j] = dpp_ror<1>((fr == 15) ? upp[j] : up[j]); u2[j] = dpp_ror<2>((fr >= 14) ? upp[j] : up[j]);
;                     }
;                     const f32x4 hcg = gb + gw0 * g2 + gw1 * g1 + gw2 * g, hcu = ub + uw0 * u2 + uw1 * u1 + uw2 * up;
;                     f32x4 a;
; #pragma unroll
;                     for (int j = 0; j < 4; ++j) a[j] = hcg[j] * __builtin_amdgcn_rcpf(1.f + __builtin_amdgcn_exp2f(-1.4426950408889634f * hcg[j])) * hcu[j];
;                     if (rt >= 2) { u32x2 w; w.x = cvt_pk_bf16(a[0], a[1]); w.y = cvt_pk_bf16(a[2], a[3]); *(u32x2*)(act + ((size_t)u.pm * 256 + rt) * DFF + ch) = w; }
.LBB0_702:
	s_or_b64 exec, exec, s[18:19]
	s_waitcnt lgkmcnt(1)
	v_cndmask_b32_e64 v0, v94, v98, s[42:43]
	v_cndmask_b32_e64 v244, v94, v98, s[40:41]
	s_waitcnt lgkmcnt(0)
	v_mov_b32_dpp v150, v0 row_ror:1 row_mask:0xf bank_mask:0xf
	v_mov_b32_dpp v152, v244 row_ror:2 row_mask:0xf bank_mask:0xf
	v_cndmask_b32_e64 v245, v90, v102, s[42:43]
	v_cndmask_b32_e64 v0, v90, v102, s[40:41]
	v_cndmask_b32_e64 v244, v95, v99, s[42:43]
	v_mov_b32_dpp v108, v245 row_ror:1 row_mask:0xf bank_mask:0xf
	v_mov_b32_dpp v148, v0 row_ror:2 row_mask:0xf bank_mask:0xf
	v_mov_b32_dpp v151, v244 row_ror:1 row_mask:0xf bank_mask:0xf
	v_cndmask_b32_e64 v245, v95, v99, s[40:41]
	v_cndmask_b32_e64 v0, v91, v103, s[42:43]
	v_lshl_add_u64 v[106:107], s[16:17], 0, v[188:189]
	v_mov_b32_dpp v153, v245 row_ror:2 row_mask:0xf bank_mask:0xf
	v_mov_b32_dpp v109, v0 row_ror:1 row_mask:0xf bank_mask:0xf
	v_cndmask_b32_e64 v244, v91, v103, s[40:41]
	v_cndmask_b32_e64 v245, v96, v100, s[42:43]
	v_cndmask_b32_e64 v0, v96, v100, s[40:41]
	v_mov_b32_dpp v149, v244 row_ror:2 row_mask:0xf bank_mask:0xf
	v_mov_b32_dpp v102, v245 row_ror:1 row_mask:0xf bank_mask:0xf
	v_mov_b32_dpp v110, v0 row_ror:2 row_mask:0xf bank_mask:0xf
	v_cndmask_b32_e64 v244, v92, v104, s[42:43]
	v_cndmask_b32_e64 v245, v92, v104, s[40:41]
	v_cndmask_b32_e64 v0, v97, v101, s[42:43]
	v_mov_b32_dpp v98, v244 row_ror:1 row_mask:0xf bank_mask:0xf
	v_mov_b32_dpp v100, v245 row_ror:2 row_mask:0xf bank_mask:0xf
	v_mov_b32_dpp v103, v0 row_ror:1 row_mask:0xf bank_mask:0xf
	v_cndmask_b32_e64 v244, v97, v101, s[40:41]
	v_cndmask_b32_e64 v245, v93, v105, s[42:43]
	v_cndmask_b32_e64 v0, v93, v105, s[40:41]
	v_mov_b32_dpp v111, v244 row_ror:2 row_mask:0xf bank_mask:0xf
	v_mov_b32_dpp v99, v245 row_ror:1 row_mask:0xf bank_mask:0xf
	v_mov_b32_dpp v101, v0 row_ror:2 row_mask:0xf bank_mask:0xf
	s_and_saveexec_b64 s[18:19], s[46:47]
	s_cbranch_execz .LBB0_704
	s_waitcnt vmcnt(4)
	v_pk_fma_f32 v[104:105], v[130:131], v[152:153], v[142:143]
	v_pk_fma_f32 v[110:111], v[132:133], v[110:111], v[144:145]
	v_pk_fma_f32 v[104:105], v[134:135], v[150:151], v[104:105]
	v_pk_fma_f32 v[102:103], v[136:137], v[102:103], v[110:111]
	v_pk_fma_f32 v[104:105], v[94:95], v[138:139], v[104:105]
	v_pk_fma_f32 v[102:103], v[96:97], v[140:141], v[102:103]
	v_mul_f32_e32 v0, 0xbfb8aa3b, v104
	v_exp_f32_e32 v0, v0
	v_mul_f32_e32 v150, 0xbfb8aa3b, v105
	v_exp_f32_e32 v150, v150
	v_mul_f32_e32 v110, 0xbfb8aa3b, v103
	v_add_f32_e32 v0, 1.0, v0
	v_exp_f32_e32 v110, v110
	v_add_f32_e32 v151, 1.0, v150
	v_rcp_f32_e32 v150, v0
	v_mul_f32_e32 v0, 0xbfb8aa3b, v102
	v_rcp_f32_e32 v151, v151
	v_exp_f32_e32 v0, v0
	s_waitcnt vmcnt(0)
	v_pk_fma_f32 v[148:149], v[114:115], v[148:149], v[126:127]
	v_pk_fma_f32 v[100:101], v[116:117], v[100:101], v[128:129]
	v_pk_fma_f32 v[108:109], v[118:119], v[108:109], v[148:149]
	v_pk_mul_f32 v[104:105], v[104:105], v[150:151]
	v_pk_fma_f32 v[108:109], v[90:91], v[122:123], v[108:109]
	v_add_f32_e32 v0, 1.0, v0
	v_pk_mul_f32 v[104:105], v[108:109], v[104:105]
	v_rcp_f32_e32 v108, v0
	v_add_f32_e32 v0, 1.0, v110
	v_rcp_f32_e32 v109, v0
	v_pk_fma_f32 v[98:99], v[120:121], v[98:99], v[100:101]
	v_pk_mul_f32 v[100:101], v[102:103], v[108:109]
	v_pk_fma_f32 v[98:99], v[92:93], v[124:125], v[98:99]
	s_nop 0
	v_pk_mul_f32 v[98:99], v[98:99], v[100:101]
	v_cvt_pk_bf16_f32 v100, v104, v105
	v_cvt_pk_bf16_f32 v101, v98, v99
	v_mov_b64_e32 v[98:99], s[12:13]
	v_mad_u64_u32 v[98:99], s[26:27], v106, s60, v[98:99]
	v_mad_i32_i24 v99, v107, s60, v99
	v_lshl_add_u64 v[98:99], v[202:203], 1, v[98:99]
	global_store_dwordx2 v[98:99], v[100:101], off
.LBB0_704:
	s_or_b64 exec, exec, s[18:19]
	v_cndmask_b32_e64 v0, v86, v94, s[42:43]
	v_cndmask_b32_e64 v244, v86, v94, s[40:41]
	v_cndmask_b32_e64 v245, v82, v90, s[42:43]
	v_mov_b32_dpp v102, v0 row_ror:1 row_mask:0xf bank_mask:0xf
	v_mov_b32_dpp v104, v244 row_ror:2 row_mask:0xf bank_mask:0xf
	v_mov_b32_dpp v98, v245 row_ror:1 row_mask:0xf bank_mask:0xf
	v_cndmask_b32_e64 v0, v82, v90, s[40:41]
	v_cndmask_b32_e64 v244, v87, v95, s[42:43]
	v_lshl_add_u64 v[108:109], s[16:17], 0, v[190:191]
	v_mov_b32_dpp v100, v0 row_ror:2 row_mask:0xf bank_mask:0xf
	v_mov_b32_dpp v103, v244 row_ror:1 row_mask:0xf bank_mask:0xf
	v_cndmask_b32_e64 v245, v87, v95, s[40:41]
	v_cndmask_b32_e64 v0, v83, v91, s[42:43]
	v_cndmask_b32_e64 v244, v83, v91, s[40:41]
	v_mov_b32_dpp v105, v245 row_ror:2 row_mask:0xf bank_mask:0xf
	v_mov_b32_dpp v99, v0 row_ror:1 row_mask:0xf bank_mask:0xf
	v_mov_b32_dpp v101, v244 row_ror:2 row_mask:0xf bank_mask:0xf
	v_cndmask_b32_e64 v245, v88, v96, s[42:43]
	v_cndmask_b32_e64 v0, v88, v96, s[40:41]
	v_cndmask_b32_e64 v244, v84, v92, s[42:43]
	v_mov_b32_dpp v94, v245 row_ror:1 row_mask:0xf bank_mask:0xf
	v_mov_b32_dpp v96, v0 row_ror:2 row_mask:0xf bank_mask:0xf
	v_mov_b32_dpp v90, v244 row_ror:1 row_mask:0xf bank_mask:0xf
	v_cndmask_b32_e64 v245, v84, v92, s[40:41]
	v_cndmask_b32_e64 v0, v89, v97, s[42:43]
	v_cndmask_b32_e64 v244, v89, v97, s[40:41]
	v_mov_b32_dpp v92, v245 row_ror:2 row_mask:0xf bank_mask:0xf
	v_mov_b32_dpp v95, v0 row_ror:1 row_mask:0xf bank_mask:0xf
	v_mov_b32_dpp v97, v244 row_ror:2 row_mask:0xf bank_mask:0xf
	v_cndmask_b32_e64 v245, v85, v93, s[42:43]
	v_cndmask_b32_e64 v0, v85, v93, s[40:41]
	s_nop 0
	v_mov_b32_dpp v91, v245 row_ror:1 row_mask:0xf bank_mask:0xf
	v_mov_b32_dpp v93, v0 row_ror:2 row_mask:0xf bank_mask:0xf
	s_and_saveexec_b64 s[18:19], s[48:49]
	s_cbranch_execz .LBB0_706
; __device__ __forceinline__ unsigned cvt_pk_bf16(float lo, float hi) { const f32x2_t v = {lo, hi}; const bf16x2_t b = __builtin_convertvector(v, bf16x2_t); return __builtin_bit_cast(unsigned, b); }
; template <int N> __device__ __forceinline__ float dpp_ror(float v) { return __builtin_bit_cast(float, __builtin_amdgcn_update_dpp(0, __builtin_bit_cast(int, v), 0x120 + N, 0xf, 0xf, false)); }
;     __device__ __forceinline__ void operator()(const Acc& acc, const Unit& u, int wr, int wc, int fr, int fq) const {
;     ...
;                 for (int m = 0; m < 4; ++m) {
;                     const int rt = ai * 128 + wr * 64 + m * 16 + fr;
;                     const f32x4 g = acc[ai][0][m][n], up = acc[ai][1][m][n];
;                     const f32x4 gp = (m == 0) ? hg : acc[ai][0][m == 0 ? 0 : m - 1][n], upp = (m == 0) ? hu : acc[ai][1][m == 0 ? 0 : m - 1][n];
;                     f32x4 g1, g2, u1, u2;
; #pragma unroll
;                     for (int j = 0; j < 4; ++j) {
;                         g1[j] = dpp_ror<1>((fr == 15) ? gp[j] : g[j]); g2[j] = dpp_ror<2>((fr >= 14) ? gp[j] : g[j]);
;                         u1[j] = dpp_ror<1>((fr == 15) ? upp[j] : up[j]); u2[j] = dpp_ror<2>((fr >= 14) ? upp[j] : up[j]);
;                     }
;                     const f32x4 hcg = gb + gw0 * g2 + gw1 * g1 + gw2 * g, hcu = ub + uw0 * u2 + uw1 * u1 + uw2 * up;
;                     f32x4 a;
; #pragma unroll
;                     for (int j = 0; j < 4; ++j) a[j] = hcg[j] * __builtin_amdgcn_rcpf(1.f + __builtin_amdgcn_exp2f(-1.4426950408889634f * hcg[j])) * hcu[j];
;                     if (rt >= 2) { u32x2 w; w.x = cvt_pk_bf16(a[0], a[1]); w.y = cvt_pk_bf16(a[2], a[3]); *(u32x2*)(act + ((size_t)u.pm * 256 + rt) * DFF + ch) = w; }
	s_waitcnt vmcnt(4)
	v_pk_fma_f32 v[104:105], v[130:131], v[104:105], v[142:143]
	v_pk_fma_f32 v[96:97], v[132:133], v[96:97], v[144:145]
	v_pk_fma_f32 v[102:103], v[134:135], v[102:103], v[104:105]
	v_pk_fma_f32 v[94:95], v[136:137], v[94:95], v[96:97]
	v_pk_fma_f32 v[102:103], v[86:87], v[138:139], v[102:103]
	v_pk_fma_f32 v[94:95], v[88:89], v[140:141], v[94:95]
	v_mul_f32_e32 v0, 0xbfb8aa3b, v102
	v_mul_f32_e32 v104, 0xbfb8aa3b, v103
	v_exp_f32_e32 v0, v0
	v_exp_f32_e32 v104, v104
	s_waitcnt vmcnt(0)
	v_pk_fma_f32 v[100:101], v[114:115], v[100:101], v[126:127]
	v_mul_f32_e32 v96, 0xbfb8aa3b, v95
	v_add_f32_e32 v0, 1.0, v0
	v_add_f32_e32 v105, 1.0, v104
	v_rcp_f32_e32 v104, v0
	v_rcp_f32_e32 v105, v105
	v_mul_f32_e32 v0, 0xbfb8aa3b, v94
	v_exp_f32_e32 v0, v0
	v_pk_fma_f32 v[98:99], v[118:119], v[98:99], v[100:101]
	v_pk_mul_f32 v[100:101], v[102:103], v[104:105]
	v_exp_f32_e32 v102, v96
	v_pk_fma_f32 v[98:99], v[82:83], v[122:123], v[98:99]
	v_add_f32_e32 v0, 1.0, v0
	v_pk_mul_f32 v[96:97], v[98:99], v[100:101]
	v_rcp_f32_e32 v98, v0
	v_add_f32_e32 v0, 1.0, v102
	v_rcp_f32_e32 v99, v0
	v_pk_fma_f32 v[92:93], v[116:117], v[92:93], v[128:129]
	s_nop 0
	v_pk_fma_f32 v[90:91], v[120:121], v[90:91], v[92:93]
	v_pk_mul_f32 v[92:93], v[94:95], v[98:99]
	v_pk_fma_f32 v[90:91], v[84:85], v[124:125], v[90:91]
	s_nop 0
	v_pk_mul_f32 v[90:91], v[90:91], v[92:93]
	v_cvt_pk_bf16_f32 v92, v96, v97
	v_cvt_pk_bf16_f32 v93, v90, v91
	v_mov_b64_e32 v[90:91], s[12:13]
	v_mad_u64_u32 v[90:91], s[26:27], v108, s60, v[90:91]
	v_mad_i32_i24 v91, v109, s60, v91
	v_lshl_add_u64 v[90:91], v[202:203], 1, v[90:91]
	global_store_dwordx2 v[90:91], v[92:93], off
.LBB0_706:
	s_or_b64 exec, exec, s[18:19]
	v_cndmask_b32_e64 v0, v78, v86, s[42:43]
	v_cndmask_b32_e64 v244, v78, v86, s[40:41]
	v_cndmask_b32_e64 v245, v74, v82, s[42:43]
	v_mov_b32_dpp v94, v0 row_ror:1 row_mask:0xf bank_mask:0xf
	v_mov_b32_dpp v96, v244 row_ror:2 row_mask:0xf bank_mask:0xf
	v_mov_b32_dpp v90, v245 row_ror:1 row_mask:0xf bank_mask:0xf
	v_cndmask_b32_e64 v0, v74, v82, s[40:41]
	v_cndmask_b32_e64 v244, v79, v87, s[42:43]
	v_lshl_add_u64 v[110:111], s[16:17], 0, v[192:193]
	v_mov_b32_dpp v92, v0 row_ror:2 row_mask:0xf bank_mask:0xf
	v_mov_b32_dpp v95, v244 row_ror:1 row_mask:0xf bank_mask:0xf
	v_cndmask_b32_e64 v245, v79, v87, s[40:41]
	v_cndmask_b32_e64 v0, v75, v83, s[42:43]
	v_cndmask_b32_e64 v244, v75, v83, s[40:41]
	v_mov_b32_dpp v97, v245 row_ror:2 row_mask:0xf bank_mask:0xf
	v_mov_b32_dpp v91, v0 row_ror:1 row_mask:0xf bank_mask:0xf
	v_mov_b32_dpp v93, v244 row_ror:2 row_mask:0xf bank_mask:0xf
	v_cndmask_b32_e64 v245, v80, v88, s[42:43]
	v_cndmask_b32_e64 v0, v80, v88, s[40:41]
	v_cndmask_b32_e64 v244, v76, v84, s[42:43]
	v_mov_b32_dpp v86, v245 row_ror:1 row_mask:0xf bank_mask:0xf
	v_mov_b32_dpp v88, v0 row_ror:2 row_mask:0xf bank_mask:0xf
	v_mov_b32_dpp v82, v244 row_ror:1 row_mask:0xf bank_mask:0xf
	v_cndmask_b32_e64 v245, v76, v84, s[40:41]
	v_cndmask_b32_e64 v0, v81, v89, s[42:43]
	v_cndmask_b32_e64 v244, v81, v89, s[40:41]
	v_mov_b32_dpp v84, v245 row_ror:2 row_mask:0xf bank_mask:0xf
	v_mov_b32_dpp v87, v0 row_ror:1 row_mask:0xf bank_mask:0xf
	v_mov_b32_dpp v89, v244 row_ror:2 row_mask:0xf bank_mask:0xf
	v_cndmask_b32_e64 v245, v77, v85, s[42:43]
	v_cndmask_b32_e64 v0, v77, v85, s[40:41]
	s_nop 0
	v_mov_b32_dpp v83, v245 row_ror:1 row_mask:0xf bank_mask:0xf
	v_mov_b32_dpp v85, v0 row_ror:2 row_mask:0xf bank_mask:0xf
	s_and_saveexec_b64 s[18:19], s[50:51]
	s_cbranch_execz .LBB0_708
	s_waitcnt vmcnt(4)
	v_pk_fma_f32 v[96:97], v[130:131], v[96:97], v[142:143]
	v_pk_fma_f32 v[88:89], v[132:133], v[88:89], v[144:145]
	v_pk_fma_f32 v[94:95], v[134:135], v[94:95], v[96:97]
	v_pk_fma_f32 v[86:87], v[136:137], v[86:87], v[88:89]
	v_pk_fma_f32 v[94:95], v[78:79], v[138:139], v[94:95]
	v_pk_fma_f32 v[86:87], v[80:81], v[140:141], v[86:87]
	v_mul_f32_e32 v0, 0xbfb8aa3b, v94
	v_mul_f32_e32 v96, 0xbfb8aa3b, v95
	v_exp_f32_e32 v0, v0
	v_exp_f32_e32 v96, v96
	s_waitcnt vmcnt(0)
	v_pk_fma_f32 v[92:93], v[114:115], v[92:93], v[126:127]
	v_mul_f32_e32 v88, 0xbfb8aa3b, v87
	v_add_f32_e32 v0, 1.0, v0
	v_add_f32_e32 v97, 1.0, v96
	v_rcp_f32_e32 v96, v0
	v_rcp_f32_e32 v97, v97
	v_mul_f32_e32 v0, 0xbfb8aa3b, v86
	v_exp_f32_e32 v0, v0
	v_pk_fma_f32 v[90:91], v[118:119], v[90:91], v[92:93]
	v_pk_mul_f32 v[92:93], v[94:95], v[96:97]
	v_exp_f32_e32 v94, v88
	v_pk_fma_f32 v[90:91], v[74:75], v[122:123], v[90:91]
	v_add_f32_e32 v0, 1.0, v0
	v_pk_mul_f32 v[88:89], v[90:91], v[92:93]
	v_rcp_f32_e32 v90, v0
	v_add_f32_e32 v0, 1.0, v94
	v_rcp_f32_e32 v91, v0
	v_pk_fma_f32 v[84:85], v[116:117], v[84:85], v[128:129]
	s_nop 0
	v_pk_fma_f32 v[82:83], v[120:121], v[82:83], v[84:85]
	v_pk_mul_f32 v[84:85], v[86:87], v[90:91]
	v_pk_fma_f32 v[82:83], v[76:77], v[124:125], v[82:83]
	s_nop 0
	v_pk_mul_f32 v[82:83], v[82:83], v[84:85]
	v_cvt_pk_bf16_f32 v84, v88, v89
	v_cvt_pk_bf16_f32 v85, v82, v83
	v_mov_b64_e32 v[82:83], s[12:13]
	v_mad_u64_u32 v[82:83], s[26:27], v110, s60, v[82:83]
	v_mad_i32_i24 v83, v111, s60, v83
	v_lshl_add_u64 v[82:83], v[202:203], 1, v[82:83]
	global_store_dwordx2 v[82:83], v[84:85], off
; __device__ __forceinline__ unsigned cvt_pk_bf16(float lo, float hi) { const f32x2_t v = {lo, hi}; const bf16x2_t b = __builtin_convertvector(v, bf16x2_t); return __builtin_bit_cast(unsigned, b); }
; template <int N> __device__ __forceinline__ float dpp_ror(float v) { return __builtin_bit_cast(float, __builtin_amdgcn_update_dpp(0, __builtin_bit_cast(int, v), 0x120 + N, 0xf, 0xf, false)); }
;     __device__ __forceinline__ void operator()(const Acc& acc, const Unit& u, int wr, int wc, int fr, int fq) const {
;     ...
;                 for (int m = 0; m < 4; ++m) {
;                     const int rt = ai * 128 + wr * 64 + m * 16 + fr;
;                     const f32x4 g = acc[ai][0][m][n], up = acc[ai][1][m][n];
;                     const f32x4 gp = (m == 0) ? hg : acc[ai][0][m == 0 ? 0 : m - 1][n], upp = (m == 0) ? hu : acc[ai][1][m == 0 ? 0 : m - 1][n];
;                     f32x4 g1, g2, u1, u2;
; #pragma unroll
;                     for (int j = 0; j < 4; ++j) {
;                         g1[j] = dpp_ror<1>((fr == 15) ? gp[j] : g[j]); g2[j] = dpp_ror<2>((fr >= 14) ? gp[j] : g[j]);
;                         u1[j] = dpp_ror<1>((fr == 15) ? upp[j] : up[j]); u2[j] = dpp_ror<2>((fr >= 14) ? upp[j] : up[j]);
;                     }
;                     const f32x4 hcg = gb + gw0 * g2 + gw1 * g1 + gw2 * g, hcu = ub + uw0 * u2 + uw1 * u1 + uw2 * up;
;                     f32x4 a;
; #pragma unroll
;                     for (int j = 0; j < 4; ++j) a[j] = hcg[j] * __builtin_amdgcn_rcpf(1.f + __builtin_amdgcn_exp2f(-1.4426950408889634f * hcg[j])) * hcu[j];
;                     if (rt >= 2) { u32x2 w; w.x = cvt_pk_bf16(a[0], a[1]); w.y = cvt_pk_bf16(a[2], a[3]); *(u32x2*)(act + ((size_t)u.pm * 256 + rt) * DFF + ch) = w; }
.LBB0_708:
	s_or_b64 exec, exec, s[18:19]
	v_cndmask_b32_e64 v0, v70, v78, s[42:43]
	v_cndmask_b32_e64 v244, v70, v78, s[40:41]
	v_cndmask_b32_e64 v245, v66, v74, s[42:43]
	v_mov_b32_dpp v86, v0 row_ror:1 row_mask:0xf bank_mask:0xf
	v_mov_b32_dpp v88, v244 row_ror:2 row_mask:0xf bank_mask:0xf
	v_mov_b32_dpp v82, v245 row_ror:1 row_mask:0xf bank_mask:0xf
	v_cndmask_b32_e64 v0, v66, v74, s[40:41]
	v_cndmask_b32_e64 v244, v71, v79, s[42:43]
	v_lshl_add_u64 v[148:149], s[16:17], 0, v[194:195]
	v_mov_b32_dpp v84, v0 row_ror:2 row_mask:0xf bank_mask:0xf
	v_mov_b32_dpp v87, v244 row_ror:1 row_mask:0xf bank_mask:0xf
	v_cndmask_b32_e64 v245, v71, v79, s[40:41]
	v_cndmask_b32_e64 v0, v67, v75, s[42:43]
	v_cndmask_b32_e64 v244, v67, v75, s[40:41]
	v_mov_b32_dpp v89, v245 row_ror:2 row_mask:0xf bank_mask:0xf
	v_mov_b32_dpp v83, v0 row_ror:1 row_mask:0xf bank_mask:0xf
	v_mov_b32_dpp v85, v244 row_ror:2 row_mask:0xf bank_mask:0xf
	v_cndmask_b32_e64 v245, v72, v80, s[42:43]
	v_cndmask_b32_e64 v0, v72, v80, s[40:41]
	v_cndmask_b32_e64 v244, v68, v76, s[42:43]
	v_mov_b32_dpp v78, v245 row_ror:1 row_mask:0xf bank_mask:0xf
	v_mov_b32_dpp v80, v0 row_ror:2 row_mask:0xf bank_mask:0xf
	v_mov_b32_dpp v74, v244 row_ror:1 row_mask:0xf bank_mask:0xf
	v_cndmask_b32_e64 v245, v68, v76, s[40:41]
	v_cndmask_b32_e64 v0, v73, v81, s[42:43]
	v_cndmask_b32_e64 v244, v73, v81, s[40:41]
	v_mov_b32_dpp v76, v245 row_ror:2 row_mask:0xf bank_mask:0xf
	v_mov_b32_dpp v79, v0 row_ror:1 row_mask:0xf bank_mask:0xf
	v_mov_b32_dpp v81, v244 row_ror:2 row_mask:0xf bank_mask:0xf
	v_cndmask_b32_e64 v245, v69, v77, s[42:43]
	v_cndmask_b32_e64 v0, v69, v77, s[40:41]
	s_nop 0
	v_mov_b32_dpp v75, v245 row_ror:1 row_mask:0xf bank_mask:0xf
	v_mov_b32_dpp v77, v0 row_ror:2 row_mask:0xf bank_mask:0xf
	s_and_saveexec_b64 s[16:17], s[52:53]
	s_cbranch_execz .LBB0_710
	s_waitcnt vmcnt(4)
	v_pk_fma_f32 v[88:89], v[130:131], v[88:89], v[142:143]
	v_pk_fma_f32 v[80:81], v[132:133], v[80:81], v[144:145]
	v_pk_fma_f32 v[86:87], v[134:135], v[86:87], v[88:89]
	v_pk_fma_f32 v[78:79], v[136:137], v[78:79], v[80:81]
	v_pk_fma_f32 v[70:71], v[70:71], v[138:139], v[86:87]
	v_pk_fma_f32 v[72:73], v[72:73], v[140:141], v[78:79]
	v_mul_f32_e32 v0, 0xbfb8aa3b, v70
	v_exp_f32_e32 v0, v0
	v_mul_f32_e32 v86, 0xbfb8aa3b, v71
	v_exp_f32_e32 v86, v86
	v_mul_f32_e32 v78, 0xbfb8aa3b, v73
	v_add_f32_e32 v0, 1.0, v0
	v_exp_f32_e32 v78, v78
	v_add_f32_e32 v87, 1.0, v86
	v_rcp_f32_e32 v86, v0
	v_mul_f32_e32 v0, 0xbfb8aa3b, v72
	v_rcp_f32_e32 v87, v87
	v_exp_f32_e32 v0, v0
	s_waitcnt vmcnt(0)
	v_pk_fma_f32 v[84:85], v[114:115], v[84:85], v[126:127]
	v_pk_fma_f32 v[76:77], v[116:117], v[76:77], v[128:129]
	v_pk_fma_f32 v[82:83], v[118:119], v[82:83], v[84:85]
	v_pk_mul_f32 v[70:71], v[70:71], v[86:87]
	v_pk_fma_f32 v[66:67], v[66:67], v[122:123], v[82:83]
	v_add_f32_e32 v0, 1.0, v0
	v_pk_mul_f32 v[66:67], v[66:67], v[70:71]
	v_rcp_f32_e32 v70, v0
	v_add_f32_e32 v0, 1.0, v78
	v_rcp_f32_e32 v71, v0
	v_pk_fma_f32 v[74:75], v[120:121], v[74:75], v[76:77]
	v_cvt_pk_bf16_f32 v66, v66, v67
	v_pk_fma_f32 v[68:69], v[68:69], v[124:125], v[74:75]
	v_pk_mul_f32 v[70:71], v[72:73], v[70:71]
	s_nop 0
	v_pk_mul_f32 v[68:69], v[68:69], v[70:71]
	s_nop 0
	v_cvt_pk_bf16_f32 v67, v68, v69
	v_mov_b64_e32 v[68:69], s[12:13]
	v_mad_u64_u32 v[68:69], s[18:19], v148, s60, v[68:69]
	v_mad_i32_i24 v69, v149, s60, v69
	v_lshl_add_u64 v[68:69], v[202:203], 1, v[68:69]
	global_store_dwordx2 v[68:69], v[66:67], off

; __device__ __forceinline__ unsigned cvt_pk_bf16(float lo, float hi) { const f32x2_t v = {lo, hi}; const bf16x2_t b = __builtin_convertvector(v, bf16x2_t); return __builtin_bit_cast(unsigned, b); }
; template <int N> __device__ __forceinline__ float dpp_ror(float v) { return __builtin_bit_cast(float, __builtin_amdgcn_update_dpp(0, __builtin_bit_cast(int, v), 0x120 + N, 0xf, 0xf, false)); }
;     __device__ __forceinline__ void operator()(const Acc& acc, const Unit& u, int wr, int wc, int fr, int fq) const {
;     ...
;                 for (int m = 0; m < 4; ++m) {
;                     const int rt = ai * 128 + wr * 64 + m * 16 + fr;
;                     const f32x4 g = acc[ai][0][m][n], up = acc[ai][1][m][n];
;                     const f32x4 gp = (m == 0) ? hg : acc[ai][0][m == 0 ? 0 : m - 1][n], upp = (m == 0) ? hu : acc[ai][1][m == 0 ? 0 : m - 1][n];
;                     f32x4 g1, g2, u1, u2;
; #pragma unroll
;                     for (int j = 0; j < 4; ++j) {
;                         g1[j] = dpp_ror<1>((fr == 15) ? gp[j] : g[j]); g2[j] = dpp_ror<2>((fr >= 14) ? gp[j] : g[j]);
;                         u1[j] = dpp_ror<1>((fr == 15) ? upp[j] : up[j]); u2[j] = dpp_ror<2>((fr >= 14) ? upp[j] : up[j]);
;                     }
;                     const f32x4 hcg = gb + gw0 * g2 + gw1 * g1 + gw2 * g, hcu = ub + uw0 * u2 + uw1 * u1 + uw2 * up;
;                     f32x4 a;
; #pragma unroll
;                     for (int j = 0; j < 4; ++j) a[j] = hcg[j] * __builtin_amdgcn_rcpf(1.f + __builtin_amdgcn_exp2f(-1.4426950408889634f * hcg[j])) * hcu[j];
;                     if (rt >= 2) { u32x2 w; w.x = cvt_pk_bf16(a[0], a[1]); w.y = cvt_pk_bf16(a[2], a[3]); *(u32x2*)(act + ((size_t)u.pm * 256 + rt) * DFF + ch) = w; }
.LBB0_712:
	s_or_b64 exec, exec, s[16:17]
	s_waitcnt lgkmcnt(1)
	v_cndmask_b32_e64 v0, v62, v98, s[42:43]
	s_waitcnt vmcnt(10)
	s_waitcnt vmcnt(9)
	v_mov_b32_dpp v120, v0 row_ror:1 row_mask:0xf bank_mask:0xf
	v_cndmask_b32_e64 v244, v62, v98, s[40:41]
	s_waitcnt lgkmcnt(0)
	v_cndmask_b32_e64 v245, v58, v102, s[42:43]
	v_mov_b32_dpp v122, v244 row_ror:2 row_mask:0xf bank_mask:0xf
	v_cndmask_b32_e64 v0, v58, v102, s[40:41]
	v_mov_b32_dpp v114, v245 row_ror:1 row_mask:0xf bank_mask:0xf
	v_cndmask_b32_e64 v244, v63, v99, s[42:43]
	v_mov_b32_dpp v118, v0 row_ror:2 row_mask:0xf bank_mask:0xf
	v_cndmask_b32_e64 v245, v63, v99, s[40:41]
	v_mov_b32_dpp v121, v244 row_ror:1 row_mask:0xf bank_mask:0xf
	v_cndmask_b32_e64 v0, v59, v103, s[42:43]
	v_mov_b32_dpp v123, v245 row_ror:2 row_mask:0xf bank_mask:0xf
	v_cndmask_b32_e64 v244, v59, v103, s[40:41]
	v_mov_b32_dpp v115, v0 row_ror:1 row_mask:0xf bank_mask:0xf
	v_cndmask_b32_e64 v245, v64, v100, s[42:43]
	v_mov_b32_dpp v119, v244 row_ror:2 row_mask:0xf bank_mask:0xf
	v_cndmask_b32_e64 v0, v64, v100, s[40:41]
	v_mov_b32_dpp v102, v245 row_ror:1 row_mask:0xf bank_mask:0xf
	v_cndmask_b32_e64 v244, v60, v104, s[42:43]
	v_mov_b32_dpp v116, v0 row_ror:2 row_mask:0xf bank_mask:0xf
	v_cndmask_b32_e64 v245, v60, v104, s[40:41]
	v_mov_b32_dpp v98, v244 row_ror:1 row_mask:0xf bank_mask:0xf
	v_cndmask_b32_e64 v0, v65, v101, s[42:43]
	v_mov_b32_dpp v100, v245 row_ror:2 row_mask:0xf bank_mask:0xf
	v_cndmask_b32_e64 v244, v65, v101, s[40:41]
	v_mov_b32_dpp v103, v0 row_ror:1 row_mask:0xf bank_mask:0xf
	v_cndmask_b32_e64 v245, v61, v105, s[42:43]
	v_mov_b32_dpp v117, v244 row_ror:2 row_mask:0xf bank_mask:0xf
	v_cndmask_b32_e64 v0, v61, v105, s[40:41]
	v_mov_b32_dpp v99, v245 row_ror:1 row_mask:0xf bank_mask:0xf
	s_nop 0
	v_mov_b32_dpp v101, v0 row_ror:2 row_mask:0xf bank_mask:0xf
	s_and_saveexec_b64 s[16:17], s[44:45]
	s_cbranch_execz .LBB0_714
	s_waitcnt vmcnt(4)
	v_pk_fma_f32 v[104:105], v[82:83], v[122:123], v[94:95]
	v_pk_fma_f32 v[116:117], v[84:85], v[116:117], v[96:97]
	v_pk_fma_f32 v[104:105], v[86:87], v[120:121], v[104:105]
	v_pk_fma_f32 v[102:103], v[88:89], v[102:103], v[116:117]
	v_pk_fma_f32 v[104:105], v[62:63], v[90:91], v[104:105]
	v_pk_fma_f32 v[102:103], v[64:65], v[92:93], v[102:103]
	v_mul_f32_e32 v0, 0xbfb8aa3b, v104
	v_exp_f32_e32 v0, v0
	v_mul_f32_e32 v120, 0xbfb8aa3b, v105
	v_exp_f32_e32 v120, v120
	v_mul_f32_e32 v116, 0xbfb8aa3b, v103
	v_add_f32_e32 v0, 1.0, v0
	v_exp_f32_e32 v116, v116
	v_add_f32_e32 v121, 1.0, v120
	v_rcp_f32_e32 v120, v0
	v_mul_f32_e32 v0, 0xbfb8aa3b, v102
	v_rcp_f32_e32 v121, v121
	v_exp_f32_e32 v0, v0
	s_waitcnt vmcnt(0)
	v_pk_fma_f32 v[118:119], v[66:67], v[118:119], v[78:79]
	v_pk_fma_f32 v[100:101], v[68:69], v[100:101], v[80:81]
	v_pk_fma_f32 v[114:115], v[70:71], v[114:115], v[118:119]
	v_pk_mul_f32 v[104:105], v[104:105], v[120:121]
	v_pk_fma_f32 v[114:115], v[58:59], v[74:75], v[114:115]
	v_add_f32_e32 v0, 1.0, v0
	v_pk_mul_f32 v[104:105], v[114:115], v[104:105]
	v_rcp_f32_e32 v114, v0
	v_add_f32_e32 v0, 1.0, v116
	v_rcp_f32_e32 v115, v0
	v_pk_fma_f32 v[98:99], v[72:73], v[98:99], v[100:101]
	v_pk_mul_f32 v[100:101], v[102:103], v[114:115]
	v_pk_fma_f32 v[98:99], v[60:61], v[76:77], v[98:99]
	s_nop 0
	v_pk_mul_f32 v[98:99], v[98:99], v[100:101]
	v_cvt_pk_bf16_f32 v100, v104, v105
	v_cvt_pk_bf16_f32 v101, v98, v99
	v_mov_b64_e32 v[98:99], s[12:13]
	v_mad_u64_u32 v[98:99], s[18:19], v162, s60, v[98:99]
	v_mad_i32_i24 v99, v163, s60, v99
	v_lshl_add_u64 v[98:99], v[202:203], 1, v[98:99]
	global_store_dwordx2 v[98:99], v[100:101], off offset:8
.LBB0_714:
	s_or_b64 exec, exec, s[16:17]
	v_cndmask_b32_e64 v0, v54, v62, s[42:43]
	v_cndmask_b32_e64 v244, v54, v62, s[40:41]
	v_cndmask_b32_e64 v245, v50, v58, s[42:43]
	v_mov_b32_dpp v102, v0 row_ror:1 row_mask:0xf bank_mask:0xf
	v_mov_b32_dpp v104, v244 row_ror:2 row_mask:0xf bank_mask:0xf
	v_mov_b32_dpp v98, v245 row_ror:1 row_mask:0xf bank_mask:0xf
	v_cndmask_b32_e64 v0, v50, v58, s[40:41]
	v_cndmask_b32_e64 v244, v55, v63, s[42:43]
	s_and_b64 vcc, exec, s[56:57]
	v_mov_b32_dpp v100, v0 row_ror:2 row_mask:0xf bank_mask:0xf
	v_mov_b32_dpp v103, v244 row_ror:1 row_mask:0xf bank_mask:0xf
	v_cndmask_b32_e64 v245, v55, v63, s[40:41]
	v_cndmask_b32_e64 v0, v51, v59, s[42:43]
	v_cndmask_b32_e64 v244, v51, v59, s[40:41]
	v_mov_b32_dpp v105, v245 row_ror:2 row_mask:0xf bank_mask:0xf
	v_mov_b32_dpp v99, v0 row_ror:1 row_mask:0xf bank_mask:0xf
	v_mov_b32_dpp v101, v244 row_ror:2 row_mask:0xf bank_mask:0xf
	v_cndmask_b32_e64 v245, v56, v64, s[42:43]
	v_cndmask_b32_e64 v0, v56, v64, s[40:41]
	v_cndmask_b32_e64 v244, v52, v60, s[42:43]
	v_mov_b32_dpp v62, v245 row_ror:1 row_mask:0xf bank_mask:0xf
	v_mov_b32_dpp v64, v0 row_ror:2 row_mask:0xf bank_mask:0xf
	v_mov_b32_dpp v58, v244 row_ror:1 row_mask:0xf bank_mask:0xf
	v_cndmask_b32_e64 v245, v52, v60, s[40:41]
	v_cndmask_b32_e64 v0, v57, v65, s[42:43]
	v_cndmask_b32_e64 v244, v57, v65, s[40:41]
	v_mov_b32_dpp v60, v245 row_ror:2 row_mask:0xf bank_mask:0xf
	v_mov_b32_dpp v63, v0 row_ror:1 row_mask:0xf bank_mask:0xf
	v_mov_b32_dpp v65, v244 row_ror:2 row_mask:0xf bank_mask:0xf
	v_cndmask_b32_e64 v245, v53, v61, s[42:43]
	v_cndmask_b32_e64 v0, v53, v61, s[40:41]
	s_nop 0
	v_mov_b32_dpp v59, v245 row_ror:1 row_mask:0xf bank_mask:0xf
	v_mov_b32_dpp v61, v0 row_ror:2 row_mask:0xf bank_mask:0xf
	s_cbranch_vccnz .LBB0_716
	s_waitcnt vmcnt(4)
	v_pk_fma_f32 v[104:105], v[82:83], v[104:105], v[94:95]
	v_pk_fma_f32 v[64:65], v[84:85], v[64:65], v[96:97]
	v_pk_fma_f32 v[102:103], v[86:87], v[102:103], v[104:105]
	v_pk_fma_f32 v[62:63], v[88:89], v[62:63], v[64:65]
	v_pk_fma_f32 v[102:103], v[54:55], v[90:91], v[102:103]
	v_pk_fma_f32 v[62:63], v[56:57], v[92:93], v[62:63]
	v_mul_f32_e32 v0, 0xbfb8aa3b, v102
	v_mul_f32_e32 v104, 0xbfb8aa3b, v103
	v_exp_f32_e32 v0, v0
	v_exp_f32_e32 v104, v104
	s_waitcnt vmcnt(0)
	v_pk_fma_f32 v[100:101], v[66:67], v[100:101], v[78:79]
	v_mul_f32_e32 v64, 0xbfb8aa3b, v63
	v_add_f32_e32 v0, 1.0, v0
	v_add_f32_e32 v105, 1.0, v104
	v_rcp_f32_e32 v104, v0
	v_rcp_f32_e32 v105, v105
	v_mul_f32_e32 v0, 0xbfb8aa3b, v62
	v_exp_f32_e32 v0, v0
	v_pk_fma_f32 v[98:99], v[70:71], v[98:99], v[100:101]
	v_pk_mul_f32 v[100:101], v[102:103], v[104:105]
	v_exp_f32_e32 v102, v64
	v_pk_fma_f32 v[98:99], v[50:51], v[74:75], v[98:99]
	v_add_f32_e32 v0, 1.0, v0
	v_pk_mul_f32 v[64:65], v[98:99], v[100:101]
	v_rcp_f32_e32 v98, v0
	v_add_f32_e32 v0, 1.0, v102
	v_rcp_f32_e32 v99, v0
	v_pk_fma_f32 v[60:61], v[68:69], v[60:61], v[80:81]
	s_nop 0
	v_pk_fma_f32 v[58:59], v[72:73], v[58:59], v[60:61]
	v_pk_mul_f32 v[60:61], v[62:63], v[98:99]
	v_pk_fma_f32 v[58:59], v[52:53], v[76:77], v[58:59]
	s_nop 0
	v_pk_mul_f32 v[58:59], v[58:59], v[60:61]
	v_cvt_pk_bf16_f32 v60, v64, v65
	v_cvt_pk_bf16_f32 v61, v58, v59
	v_mov_b64_e32 v[58:59], s[12:13]
	v_mad_u64_u32 v[58:59], s[16:17], v154, s60, v[58:59]
	v_mad_i32_i24 v59, v155, s60, v59
	v_lshl_add_u64 v[58:59], v[202:203], 1, v[58:59]
	global_store_dwordx2 v[58:59], v[60:61], off offset:8
; __device__ __forceinline__ unsigned cvt_pk_bf16(float lo, float hi) { const f32x2_t v = {lo, hi}; const bf16x2_t b = __builtin_convertvector(v, bf16x2_t); return __builtin_bit_cast(unsigned, b); }
; template <int N> __device__ __forceinline__ float dpp_ror(float v) { return __builtin_bit_cast(float, __builtin_amdgcn_update_dpp(0, __builtin_bit_cast(int, v), 0x120 + N, 0xf, 0xf, false)); }
;     __device__ __forceinline__ void operator()(const Acc& acc, const Unit& u, int wr, int wc, int fr, int fq) const {
;     ...
;                 for (int m = 0; m < 4; ++m) {
;                     const int rt = ai * 128 + wr * 64 + m * 16 + fr;
;                     const f32x4 g = acc[ai][0][m][n], up = acc[ai][1][m][n];
;                     const f32x4 gp = (m == 0) ? hg : acc[ai][0][m == 0 ? 0 : m - 1][n], upp = (m == 0) ? hu : acc[ai][1][m == 0 ? 0 : m - 1][n];
;                     f32x4 g1, g2, u1, u2;
; #pragma unroll
;                     for (int j = 0; j < 4; ++j) {
;                         g1[j] = dpp_ror<1>((fr == 15) ? gp[j] : g[j]); g2[j] = dpp_ror<2>((fr >= 14) ? gp[j] : g[j]);
;                         u1[j] = dpp_ror<1>((fr == 15) ? upp[j] : up[j]); u2[j] = dpp_ror<2>((fr >= 14) ? upp[j] : up[j]);
;                     }
;                     const f32x4 hcg = gb + gw0 * g2 + gw1 * g1 + gw2 * g, hcu = ub + uw0 * u2 + uw1 * u1 + uw2 * up;
;                     f32x4 a;
; #pragma unroll
;                     for (int j = 0; j < 4; ++j) a[j] = hcg[j] * __builtin_amdgcn_rcpf(1.f + __builtin_amdgcn_exp2f(-1.4426950408889634f * hcg[j])) * hcu[j];
;                     if (rt >= 2) { u32x2 w; w.x = cvt_pk_bf16(a[0], a[1]); w.y = cvt_pk_bf16(a[2], a[3]); *(u32x2*)(act + ((size_t)u.pm * 256 + rt) * DFF + ch) = w; }
.LBB0_716:
	v_cndmask_b32_e64 v0, v46, v54, s[42:43]
	v_cndmask_b32_e64 v244, v46, v54, s[40:41]
	v_cndmask_b32_e64 v245, v42, v50, s[42:43]
	v_mov_b32_dpp v62, v0 row_ror:1 row_mask:0xf bank_mask:0xf
	v_mov_b32_dpp v64, v244 row_ror:2 row_mask:0xf bank_mask:0xf
	v_mov_b32_dpp v58, v245 row_ror:1 row_mask:0xf bank_mask:0xf
	v_cndmask_b32_e64 v0, v42, v50, s[40:41]
	v_cndmask_b32_e64 v244, v47, v55, s[42:43]
	s_and_b64 vcc, exec, s[56:57]
	v_mov_b32_dpp v60, v0 row_ror:2 row_mask:0xf bank_mask:0xf
	v_mov_b32_dpp v63, v244 row_ror:1 row_mask:0xf bank_mask:0xf
	v_cndmask_b32_e64 v245, v47, v55, s[40:41]
	v_cndmask_b32_e64 v0, v43, v51, s[42:43]
	v_cndmask_b32_e64 v244, v43, v51, s[40:41]
	v_mov_b32_dpp v65, v245 row_ror:2 row_mask:0xf bank_mask:0xf
	v_mov_b32_dpp v59, v0 row_ror:1 row_mask:0xf bank_mask:0xf
	v_mov_b32_dpp v61, v244 row_ror:2 row_mask:0xf bank_mask:0xf
	v_cndmask_b32_e64 v245, v48, v56, s[42:43]
	v_cndmask_b32_e64 v0, v48, v56, s[40:41]
	v_cndmask_b32_e64 v244, v44, v52, s[42:43]
	v_mov_b32_dpp v54, v245 row_ror:1 row_mask:0xf bank_mask:0xf
	v_mov_b32_dpp v56, v0 row_ror:2 row_mask:0xf bank_mask:0xf
	v_mov_b32_dpp v50, v244 row_ror:1 row_mask:0xf bank_mask:0xf
	v_cndmask_b32_e64 v245, v44, v52, s[40:41]
	v_cndmask_b32_e64 v0, v49, v57, s[42:43]
	v_cndmask_b32_e64 v244, v49, v57, s[40:41]
	v_mov_b32_dpp v52, v245 row_ror:2 row_mask:0xf bank_mask:0xf
	v_mov_b32_dpp v55, v0 row_ror:1 row_mask:0xf bank_mask:0xf
	v_mov_b32_dpp v57, v244 row_ror:2 row_mask:0xf bank_mask:0xf
	v_cndmask_b32_e64 v245, v45, v53, s[42:43]
	v_cndmask_b32_e64 v0, v45, v53, s[40:41]
	s_nop 0
	v_mov_b32_dpp v51, v245 row_ror:1 row_mask:0xf bank_mask:0xf
	v_mov_b32_dpp v53, v0 row_ror:2 row_mask:0xf bank_mask:0xf
	s_cbranch_vccnz .LBB0_718
	s_waitcnt vmcnt(4)
	v_pk_fma_f32 v[64:65], v[82:83], v[64:65], v[94:95]
	v_pk_fma_f32 v[56:57], v[84:85], v[56:57], v[96:97]
	v_pk_fma_f32 v[62:63], v[86:87], v[62:63], v[64:65]
	v_pk_fma_f32 v[54:55], v[88:89], v[54:55], v[56:57]
	v_pk_fma_f32 v[62:63], v[46:47], v[90:91], v[62:63]
	v_pk_fma_f32 v[54:55], v[48:49], v[92:93], v[54:55]
	v_mul_f32_e32 v0, 0xbfb8aa3b, v62
	v_mul_f32_e32 v64, 0xbfb8aa3b, v63
	v_exp_f32_e32 v0, v0
	v_exp_f32_e32 v64, v64
	s_waitcnt vmcnt(0)
	v_pk_fma_f32 v[60:61], v[66:67], v[60:61], v[78:79]
	v_mul_f32_e32 v56, 0xbfb8aa3b, v55
	v_add_f32_e32 v0, 1.0, v0
	v_add_f32_e32 v65, 1.0, v64
	v_rcp_f32_e32 v64, v0
	v_rcp_f32_e32 v65, v65
	v_mul_f32_e32 v0, 0xbfb8aa3b, v54
	v_exp_f32_e32 v0, v0
	v_pk_fma_f32 v[58:59], v[70:71], v[58:59], v[60:61]
	v_pk_mul_f32 v[60:61], v[62:63], v[64:65]
	v_exp_f32_e32 v62, v56
	v_pk_fma_f32 v[58:59], v[42:43], v[74:75], v[58:59]
	v_add_f32_e32 v0, 1.0, v0
	v_pk_mul_f32 v[56:57], v[58:59], v[60:61]
	v_rcp_f32_e32 v58, v0
	v_add_f32_e32 v0, 1.0, v62
	v_rcp_f32_e32 v59, v0
	v_pk_fma_f32 v[52:53], v[68:69], v[52:53], v[80:81]
	s_nop 0
	v_pk_fma_f32 v[50:51], v[72:73], v[50:51], v[52:53]
	v_pk_mul_f32 v[52:53], v[54:55], v[58:59]
	v_pk_fma_f32 v[50:51], v[44:45], v[76:77], v[50:51]
	s_nop 0
	v_pk_mul_f32 v[50:51], v[50:51], v[52:53]
	v_cvt_pk_bf16_f32 v52, v56, v57
	v_cvt_pk_bf16_f32 v53, v50, v51
	v_mov_b64_e32 v[50:51], s[12:13]
	v_mad_u64_u32 v[50:51], s[16:17], v146, s60, v[50:51]
	v_mad_i32_i24 v51, v147, s60, v51
	v_lshl_add_u64 v[50:51], v[202:203], 1, v[50:51]
	global_store_dwordx2 v[50:51], v[52:53], off offset:8
.LBB0_718:
	v_cndmask_b32_e64 v0, v38, v46, s[42:43]
	v_cndmask_b32_e64 v244, v38, v46, s[40:41]
	v_cndmask_b32_e64 v245, v34, v42, s[42:43]
	v_mov_b32_dpp v54, v0 row_ror:1 row_mask:0xf bank_mask:0xf
	v_mov_b32_dpp v56, v244 row_ror:2 row_mask:0xf bank_mask:0xf
	v_mov_b32_dpp v50, v245 row_ror:1 row_mask:0xf bank_mask:0xf
	v_cndmask_b32_e64 v0, v34, v42, s[40:41]
	v_cndmask_b32_e64 v244, v39, v47, s[42:43]
	s_and_b64 vcc, exec, s[56:57]
	v_mov_b32_dpp v52, v0 row_ror:2 row_mask:0xf bank_mask:0xf
	v_mov_b32_dpp v55, v244 row_ror:1 row_mask:0xf bank_mask:0xf
	v_cndmask_b32_e64 v245, v39, v47, s[40:41]
	v_cndmask_b32_e64 v0, v35, v43, s[42:43]
	v_cndmask_b32_e64 v244, v35, v43, s[40:41]
	v_mov_b32_dpp v57, v245 row_ror:2 row_mask:0xf bank_mask:0xf
	v_mov_b32_dpp v51, v0 row_ror:1 row_mask:0xf bank_mask:0xf
	v_mov_b32_dpp v53, v244 row_ror:2 row_mask:0xf bank_mask:0xf
	v_cndmask_b32_e64 v245, v40, v48, s[42:43]
	v_cndmask_b32_e64 v0, v40, v48, s[40:41]
	v_cndmask_b32_e64 v244, v36, v44, s[42:43]
	v_mov_b32_dpp v46, v245 row_ror:1 row_mask:0xf bank_mask:0xf
	v_mov_b32_dpp v48, v0 row_ror:2 row_mask:0xf bank_mask:0xf
	v_mov_b32_dpp v42, v244 row_ror:1 row_mask:0xf bank_mask:0xf
	v_cndmask_b32_e64 v245, v36, v44, s[40:41]
	v_cndmask_b32_e64 v0, v41, v49, s[42:43]
	v_cndmask_b32_e64 v244, v41, v49, s[40:41]
	v_mov_b32_dpp v44, v245 row_ror:2 row_mask:0xf bank_mask:0xf
	v_mov_b32_dpp v47, v0 row_ror:1 row_mask:0xf bank_mask:0xf
	v_mov_b32_dpp v49, v244 row_ror:2 row_mask:0xf bank_mask:0xf
	v_cndmask_b32_e64 v245, v37, v45, s[42:43]
	v_cndmask_b32_e64 v0, v37, v45, s[40:41]
	s_nop 0
	v_mov_b32_dpp v43, v245 row_ror:1 row_mask:0xf bank_mask:0xf
	v_mov_b32_dpp v45, v0 row_ror:2 row_mask:0xf bank_mask:0xf
	s_cbranch_vccnz .LBB0_720
	s_waitcnt vmcnt(4)
	v_pk_fma_f32 v[56:57], v[82:83], v[56:57], v[94:95]
	v_pk_fma_f32 v[48:49], v[84:85], v[48:49], v[96:97]
	v_pk_fma_f32 v[54:55], v[86:87], v[54:55], v[56:57]
	v_pk_fma_f32 v[46:47], v[88:89], v[46:47], v[48:49]
	v_pk_fma_f32 v[38:39], v[38:39], v[90:91], v[54:55]
	v_pk_fma_f32 v[40:41], v[40:41], v[92:93], v[46:47]
	v_mul_f32_e32 v0, 0xbfb8aa3b, v38
	v_exp_f32_e32 v0, v0
	v_mul_f32_e32 v54, 0xbfb8aa3b, v39
	v_exp_f32_e32 v54, v54
	v_mul_f32_e32 v46, 0xbfb8aa3b, v41
	v_add_f32_e32 v0, 1.0, v0
	v_exp_f32_e32 v46, v46
	v_add_f32_e32 v55, 1.0, v54
	v_rcp_f32_e32 v54, v0
	v_mul_f32_e32 v0, 0xbfb8aa3b, v40
	v_rcp_f32_e32 v55, v55
	v_exp_f32_e32 v0, v0
	s_waitcnt vmcnt(0)
	v_pk_fma_f32 v[52:53], v[66:67], v[52:53], v[78:79]
	v_pk_fma_f32 v[44:45], v[68:69], v[44:45], v[80:81]
	v_pk_fma_f32 v[50:51], v[70:71], v[50:51], v[52:53]
	v_pk_mul_f32 v[38:39], v[38:39], v[54:55]
	v_pk_fma_f32 v[34:35], v[34:35], v[74:75], v[50:51]
	v_add_f32_e32 v0, 1.0, v0
	v_pk_mul_f32 v[34:35], v[34:35], v[38:39]
	v_rcp_f32_e32 v38, v0
	v_add_f32_e32 v0, 1.0, v46
	v_rcp_f32_e32 v39, v0
	v_pk_fma_f32 v[42:43], v[72:73], v[42:43], v[44:45]
	v_cvt_pk_bf16_f32 v34, v34, v35
	v_pk_fma_f32 v[36:37], v[36:37], v[76:77], v[42:43]
	v_pk_mul_f32 v[38:39], v[40:41], v[38:39]
	s_nop 0
	v_pk_mul_f32 v[36:37], v[36:37], v[38:39]
	s_nop 0
	v_cvt_pk_bf16_f32 v35, v36, v37
	v_mov_b64_e32 v[36:37], s[12:13]
	v_mad_u64_u32 v[36:37], s[16:17], v112, s60, v[36:37]
	v_mad_i32_i24 v37, v113, s60, v37
	v_lshl_add_u64 v[36:37], v[202:203], 1, v[36:37]
	global_store_dwordx2 v[36:37], v[34:35], off offset:8

; __device__ __forceinline__ unsigned cvt_pk_bf16(float lo, float hi) { const f32x2_t v = {lo, hi}; const bf16x2_t b = __builtin_convertvector(v, bf16x2_t); return __builtin_bit_cast(unsigned, b); }
; template <int N> __device__ __forceinline__ float dpp_ror(float v) { return __builtin_bit_cast(float, __builtin_amdgcn_update_dpp(0, __builtin_bit_cast(int, v), 0x120 + N, 0xf, 0xf, false)); }
;     __device__ __forceinline__ void operator()(const Acc& acc, const Unit& u, int wr, int wc, int fr, int fq) const {
;     ...
;                 for (int m = 0; m < 4; ++m) {
;                     const int rt = ai * 128 + wr * 64 + m * 16 + fr;
;                     const f32x4 g = acc[ai][0][m][n], up = acc[ai][1][m][n];
;                     const f32x4 gp = (m == 0) ? hg : acc[ai][0][m == 0 ? 0 : m - 1][n], upp = (m == 0) ? hu : acc[ai][1][m == 0 ? 0 : m - 1][n];
;                     f32x4 g1, g2, u1, u2;
; #pragma unroll
;                     for (int j = 0; j < 4; ++j) {
;                         g1[j] = dpp_ror<1>((fr == 15) ? gp[j] : g[j]); g2[j] = dpp_ror<2>((fr >= 14) ? gp[j] : g[j]);
;                         u1[j] = dpp_ror<1>((fr == 15) ? upp[j] : up[j]); u2[j] = dpp_ror<2>((fr >= 14) ? upp[j] : up[j]);
;                     }
;                     const f32x4 hcg = gb + gw0 * g2 + gw1 * g1 + gw2 * g, hcu = ub + uw0 * u2 + uw1 * u1 + uw2 * up;
;                     f32x4 a;
; #pragma unroll
;                     for (int j = 0; j < 4; ++j) a[j] = hcg[j] * __builtin_amdgcn_rcpf(1.f + __builtin_amdgcn_exp2f(-1.4426950408889634f * hcg[j])) * hcu[j];
;                     if (rt >= 2) { u32x2 w; w.x = cvt_pk_bf16(a[0], a[1]); w.y = cvt_pk_bf16(a[2], a[3]); *(u32x2*)(act + ((size_t)u.pm * 256 + rt) * DFF + ch) = w; }
.LBB0_722:
	s_or_b64 exec, exec, s[16:17]
	s_waitcnt lgkmcnt(1)
	v_cndmask_b32_e64 v0, v30, v34, s[42:43]
	v_cndmask_b32_e64 v244, v30, v34, s[40:41]
	s_waitcnt lgkmcnt(0)
	v_mov_b32_dpp v48, v0 row_ror:1 row_mask:0xf bank_mask:0xf
	v_mov_b32_dpp v50, v244 row_ror:2 row_mask:0xf bank_mask:0xf
	v_cndmask_b32_e64 v245, v26, v38, s[42:43]
	v_cndmask_b32_e64 v0, v26, v38, s[40:41]
	v_cndmask_b32_e64 v244, v31, v35, s[42:43]
	v_mov_b32_dpp v42, v245 row_ror:1 row_mask:0xf bank_mask:0xf
	v_mov_b32_dpp v46, v0 row_ror:2 row_mask:0xf bank_mask:0xf
	v_mov_b32_dpp v49, v244 row_ror:1 row_mask:0xf bank_mask:0xf
	v_cndmask_b32_e64 v245, v31, v35, s[40:41]
	v_cndmask_b32_e64 v0, v27, v39, s[42:43]
	v_cndmask_b32_e64 v244, v27, v39, s[40:41]
	v_mov_b32_dpp v51, v245 row_ror:2 row_mask:0xf bank_mask:0xf
	v_mov_b32_dpp v43, v0 row_ror:1 row_mask:0xf bank_mask:0xf
	v_mov_b32_dpp v47, v244 row_ror:2 row_mask:0xf bank_mask:0xf
	v_cndmask_b32_e64 v245, v32, v36, s[42:43]
	v_cndmask_b32_e64 v0, v32, v36, s[40:41]
	v_cndmask_b32_e64 v244, v28, v40, s[42:43]
	v_mov_b32_dpp v38, v245 row_ror:1 row_mask:0xf bank_mask:0xf
	v_mov_b32_dpp v44, v0 row_ror:2 row_mask:0xf bank_mask:0xf
	v_mov_b32_dpp v34, v244 row_ror:1 row_mask:0xf bank_mask:0xf
	v_cndmask_b32_e64 v245, v28, v40, s[40:41]
	v_cndmask_b32_e64 v0, v33, v37, s[42:43]
	v_cndmask_b32_e64 v244, v33, v37, s[40:41]
	v_mov_b32_dpp v36, v245 row_ror:2 row_mask:0xf bank_mask:0xf
	v_mov_b32_dpp v39, v0 row_ror:1 row_mask:0xf bank_mask:0xf
	v_mov_b32_dpp v45, v244 row_ror:2 row_mask:0xf bank_mask:0xf
	v_cndmask_b32_e64 v245, v29, v41, s[42:43]
	v_cndmask_b32_e64 v0, v29, v41, s[40:41]
	s_nop 0
	v_mov_b32_dpp v35, v245 row_ror:1 row_mask:0xf bank_mask:0xf
	v_mov_b32_dpp v37, v0 row_ror:2 row_mask:0xf bank_mask:0xf
	s_and_saveexec_b64 s[16:17], s[46:47]
	s_cbranch_execz .LBB0_724
	s_waitcnt vmcnt(4)
	v_pk_fma_f32 v[40:41], v[82:83], v[50:51], v[94:95]
	v_pk_fma_f32 v[44:45], v[84:85], v[44:45], v[96:97]
	v_pk_fma_f32 v[40:41], v[86:87], v[48:49], v[40:41]
	v_pk_fma_f32 v[38:39], v[88:89], v[38:39], v[44:45]
	v_pk_fma_f32 v[40:41], v[30:31], v[90:91], v[40:41]
	v_pk_fma_f32 v[38:39], v[32:33], v[92:93], v[38:39]
	v_mul_f32_e32 v0, 0xbfb8aa3b, v40
	v_exp_f32_e32 v0, v0
	v_mul_f32_e32 v48, 0xbfb8aa3b, v41
	v_exp_f32_e32 v48, v48
	v_mul_f32_e32 v44, 0xbfb8aa3b, v39
	v_add_f32_e32 v0, 1.0, v0
	v_exp_f32_e32 v44, v44
	v_add_f32_e32 v49, 1.0, v48
	v_rcp_f32_e32 v48, v0
	v_mul_f32_e32 v0, 0xbfb8aa3b, v38
	v_rcp_f32_e32 v49, v49
	v_exp_f32_e32 v0, v0
	s_waitcnt vmcnt(0)
	v_pk_fma_f32 v[46:47], v[66:67], v[46:47], v[78:79]
	v_pk_fma_f32 v[36:37], v[68:69], v[36:37], v[80:81]
	v_pk_fma_f32 v[42:43], v[70:71], v[42:43], v[46:47]
	v_pk_mul_f32 v[40:41], v[40:41], v[48:49]
	v_pk_fma_f32 v[42:43], v[26:27], v[74:75], v[42:43]
	v_add_f32_e32 v0, 1.0, v0
	v_pk_mul_f32 v[40:41], v[42:43], v[40:41]
	v_rcp_f32_e32 v42, v0
	v_add_f32_e32 v0, 1.0, v44
	v_rcp_f32_e32 v43, v0
	v_pk_fma_f32 v[34:35], v[72:73], v[34:35], v[36:37]
	v_pk_mul_f32 v[36:37], v[38:39], v[42:43]
	v_pk_fma_f32 v[34:35], v[28:29], v[76:77], v[34:35]
	s_nop 0
	v_pk_mul_f32 v[34:35], v[34:35], v[36:37]
	v_cvt_pk_bf16_f32 v36, v40, v41
	v_cvt_pk_bf16_f32 v37, v34, v35
	v_mov_b64_e32 v[34:35], s[12:13]
	v_mad_u64_u32 v[34:35], s[18:19], v106, s60, v[34:35]
	v_mad_i32_i24 v35, v107, s60, v35
	v_lshl_add_u64 v[34:35], v[202:203], 1, v[34:35]
	global_store_dwordx2 v[34:35], v[36:37], off offset:8
.LBB0_724:
	s_or_b64 exec, exec, s[16:17]
	v_cndmask_b32_e64 v0, v22, v30, s[42:43]
	v_cndmask_b32_e64 v244, v22, v30, s[40:41]
	v_cndmask_b32_e64 v245, v18, v26, s[42:43]
	v_mov_b32_dpp v38, v0 row_ror:1 row_mask:0xf bank_mask:0xf
	v_mov_b32_dpp v40, v244 row_ror:2 row_mask:0xf bank_mask:0xf
	v_mov_b32_dpp v34, v245 row_ror:1 row_mask:0xf bank_mask:0xf
	v_cndmask_b32_e64 v0, v18, v26, s[40:41]
	v_cndmask_b32_e64 v244, v23, v31, s[42:43]
	v_cndmask_b32_e64 v245, v23, v31, s[40:41]
	v_mov_b32_dpp v36, v0 row_ror:2 row_mask:0xf bank_mask:0xf
	v_mov_b32_dpp v39, v244 row_ror:1 row_mask:0xf bank_mask:0xf
	v_mov_b32_dpp v41, v245 row_ror:2 row_mask:0xf bank_mask:0xf
	v_cndmask_b32_e64 v0, v19, v27, s[42:43]
	v_cndmask_b32_e64 v244, v19, v27, s[40:41]
	v_cndmask_b32_e64 v245, v24, v32, s[42:43]
	v_mov_b32_dpp v35, v0 row_ror:1 row_mask:0xf bank_mask:0xf
	v_mov_b32_dpp v37, v244 row_ror:2 row_mask:0xf bank_mask:0xf
	v_mov_b32_dpp v30, v245 row_ror:1 row_mask:0xf bank_mask:0xf
	v_cndmask_b32_e64 v0, v24, v32, s[40:41]
	v_cndmask_b32_e64 v244, v20, v28, s[42:43]
	v_cndmask_b32_e64 v245, v20, v28, s[40:41]
	v_mov_b32_dpp v32, v0 row_ror:2 row_mask:0xf bank_mask:0xf
	v_mov_b32_dpp v26, v244 row_ror:1 row_mask:0xf bank_mask:0xf
	v_mov_b32_dpp v28, v245 row_ror:2 row_mask:0xf bank_mask:0xf
	v_cndmask_b32_e64 v0, v25, v33, s[42:43]
	v_cndmask_b32_e64 v244, v25, v33, s[40:41]
	v_cndmask_b32_e64 v245, v21, v29, s[42:43]
	v_mov_b32_dpp v31, v0 row_ror:1 row_mask:0xf bank_mask:0xf
	v_mov_b32_dpp v33, v244 row_ror:2 row_mask:0xf bank_mask:0xf
	v_mov_b32_dpp v27, v245 row_ror:1 row_mask:0xf bank_mask:0xf
	v_cndmask_b32_e64 v0, v21, v29, s[40:41]
	s_nop 1
	v_mov_b32_dpp v29, v0 row_ror:2 row_mask:0xf bank_mask:0xf
	s_and_saveexec_b64 s[16:17], s[48:49]
	s_cbranch_execz .LBB0_726
	s_waitcnt vmcnt(4)
	v_pk_fma_f32 v[40:41], v[82:83], v[40:41], v[94:95]
	v_pk_fma_f32 v[32:33], v[84:85], v[32:33], v[96:97]
	v_pk_fma_f32 v[38:39], v[86:87], v[38:39], v[40:41]
	v_pk_fma_f32 v[30:31], v[88:89], v[30:31], v[32:33]
	v_pk_fma_f32 v[38:39], v[22:23], v[90:91], v[38:39]
	v_pk_fma_f32 v[30:31], v[24:25], v[92:93], v[30:31]
	v_mul_f32_e32 v0, 0xbfb8aa3b, v38
	v_mul_f32_e32 v40, 0xbfb8aa3b, v39
	v_exp_f32_e32 v0, v0
	v_exp_f32_e32 v40, v40
	s_waitcnt vmcnt(0)
	v_pk_fma_f32 v[36:37], v[66:67], v[36:37], v[78:79]
	v_mul_f32_e32 v32, 0xbfb8aa3b, v31
	v_add_f32_e32 v0, 1.0, v0
	v_add_f32_e32 v41, 1.0, v40
	v_rcp_f32_e32 v40, v0
	v_rcp_f32_e32 v41, v41
	v_mul_f32_e32 v0, 0xbfb8aa3b, v30
	v_exp_f32_e32 v0, v0
	v_pk_fma_f32 v[34:35], v[70:71], v[34:35], v[36:37]
	v_pk_mul_f32 v[36:37], v[38:39], v[40:41]
	v_exp_f32_e32 v38, v32
	v_pk_fma_f32 v[34:35], v[18:19], v[74:75], v[34:35]
	v_add_f32_e32 v0, 1.0, v0
	v_pk_mul_f32 v[32:33], v[34:35], v[36:37]
	v_rcp_f32_e32 v34, v0
	v_add_f32_e32 v0, 1.0, v38
	v_rcp_f32_e32 v35, v0
	v_pk_fma_f32 v[28:29], v[68:69], v[28:29], v[80:81]
	s_nop 0
	v_pk_fma_f32 v[26:27], v[72:73], v[26:27], v[28:29]
	v_pk_mul_f32 v[28:29], v[30:31], v[34:35]
	v_pk_fma_f32 v[26:27], v[20:21], v[76:77], v[26:27]
	s_nop 0
	v_pk_mul_f32 v[26:27], v[26:27], v[28:29]
	v_cvt_pk_bf16_f32 v28, v32, v33
	v_cvt_pk_bf16_f32 v29, v26, v27
	v_mov_b64_e32 v[26:27], s[12:13]
	v_mad_u64_u32 v[26:27], s[18:19], v108, s60, v[26:27]
	v_mad_i32_i24 v27, v109, s60, v27
	v_lshl_add_u64 v[26:27], v[202:203], 1, v[26:27]
	global_store_dwordx2 v[26:27], v[28:29], off offset:8
; __device__ __forceinline__ unsigned cvt_pk_bf16(float lo, float hi) { const f32x2_t v = {lo, hi}; const bf16x2_t b = __builtin_convertvector(v, bf16x2_t); return __builtin_bit_cast(unsigned, b); }
; template <int N> __device__ __forceinline__ float dpp_ror(float v) { return __builtin_bit_cast(float, __builtin_amdgcn_update_dpp(0, __builtin_bit_cast(int, v), 0x120 + N, 0xf, 0xf, false)); }
;     __device__ __forceinline__ void operator()(const Acc& acc, const Unit& u, int wr, int wc, int fr, int fq) const {
;     ...
;                 for (int m = 0; m < 4; ++m) {
;                     const int rt = ai * 128 + wr * 64 + m * 16 + fr;
;                     const f32x4 g = acc[ai][0][m][n], up = acc[ai][1][m][n];
;                     const f32x4 gp = (m == 0) ? hg : acc[ai][0][m == 0 ? 0 : m - 1][n], upp = (m == 0) ? hu : acc[ai][1][m == 0 ? 0 : m - 1][n];
;                     f32x4 g1, g2, u1, u2;
; #pragma unroll
;                     for (int j = 0; j < 4; ++j) {
;                         g1[j] = dpp_ror<1>((fr == 15) ? gp[j] : g[j]); g2[j] = dpp_ror<2>((fr >= 14) ? gp[j] : g[j]);
;                         u1[j] = dpp_ror<1>((fr == 15) ? upp[j] : up[j]); u2[j] = dpp_ror<2>((fr >= 14) ? upp[j] : up[j]);
;                     }
;                     const f32x4 hcg = gb + gw0 * g2 + gw1 * g1 + gw2 * g, hcu = ub + uw0 * u2 + uw1 * u1 + uw2 * up;
;                     f32x4 a;
; #pragma unroll
;                     for (int j = 0; j < 4; ++j) a[j] = hcg[j] * __builtin_amdgcn_rcpf(1.f + __builtin_amdgcn_exp2f(-1.4426950408889634f * hcg[j])) * hcu[j];
;                     if (rt >= 2) { u32x2 w; w.x = cvt_pk_bf16(a[0], a[1]); w.y = cvt_pk_bf16(a[2], a[3]); *(u32x2*)(act + ((size_t)u.pm * 256 + rt) * DFF + ch) = w; }
.LBB0_726:
	s_or_b64 exec, exec, s[16:17]
	v_cndmask_b32_e64 v0, v14, v22, s[42:43]
	v_cndmask_b32_e64 v244, v14, v22, s[40:41]
	v_cndmask_b32_e64 v245, v10, v18, s[42:43]
	v_mov_b32_dpp v30, v0 row_ror:1 row_mask:0xf bank_mask:0xf
	v_mov_b32_dpp v32, v244 row_ror:2 row_mask:0xf bank_mask:0xf
	v_mov_b32_dpp v26, v245 row_ror:1 row_mask:0xf bank_mask:0xf
	v_cndmask_b32_e64 v0, v10, v18, s[40:41]
	v_cndmask_b32_e64 v244, v15, v23, s[42:43]
	v_cndmask_b32_e64 v245, v15, v23, s[40:41]
	v_mov_b32_dpp v28, v0 row_ror:2 row_mask:0xf bank_mask:0xf
	v_mov_b32_dpp v31, v244 row_ror:1 row_mask:0xf bank_mask:0xf
	v_mov_b32_dpp v33, v245 row_ror:2 row_mask:0xf bank_mask:0xf
	v_cndmask_b32_e64 v0, v11, v19, s[42:43]
	v_cndmask_b32_e64 v244, v11, v19, s[40:41]
	v_cndmask_b32_e64 v245, v16, v24, s[42:43]
	v_mov_b32_dpp v27, v0 row_ror:1 row_mask:0xf bank_mask:0xf
	v_mov_b32_dpp v29, v244 row_ror:2 row_mask:0xf bank_mask:0xf
	v_mov_b32_dpp v22, v245 row_ror:1 row_mask:0xf bank_mask:0xf
	v_cndmask_b32_e64 v0, v16, v24, s[40:41]
	v_cndmask_b32_e64 v244, v12, v20, s[42:43]
	v_cndmask_b32_e64 v245, v12, v20, s[40:41]
	v_mov_b32_dpp v24, v0 row_ror:2 row_mask:0xf bank_mask:0xf
	v_mov_b32_dpp v18, v244 row_ror:1 row_mask:0xf bank_mask:0xf
	v_mov_b32_dpp v20, v245 row_ror:2 row_mask:0xf bank_mask:0xf
	v_cndmask_b32_e64 v0, v17, v25, s[42:43]
	v_cndmask_b32_e64 v244, v17, v25, s[40:41]
	v_cndmask_b32_e64 v245, v13, v21, s[42:43]
	v_mov_b32_dpp v23, v0 row_ror:1 row_mask:0xf bank_mask:0xf
	v_mov_b32_dpp v25, v244 row_ror:2 row_mask:0xf bank_mask:0xf
	v_mov_b32_dpp v19, v245 row_ror:1 row_mask:0xf bank_mask:0xf
	v_cndmask_b32_e64 v0, v13, v21, s[40:41]
	s_nop 1
	v_mov_b32_dpp v21, v0 row_ror:2 row_mask:0xf bank_mask:0xf
	s_and_saveexec_b64 s[16:17], s[50:51]
	s_cbranch_execz .LBB0_728
	s_waitcnt vmcnt(4)
	v_pk_fma_f32 v[32:33], v[82:83], v[32:33], v[94:95]
	v_pk_fma_f32 v[24:25], v[84:85], v[24:25], v[96:97]
	v_pk_fma_f32 v[30:31], v[86:87], v[30:31], v[32:33]
	v_pk_fma_f32 v[22:23], v[88:89], v[22:23], v[24:25]
	v_pk_fma_f32 v[30:31], v[14:15], v[90:91], v[30:31]
	v_pk_fma_f32 v[22:23], v[16:17], v[92:93], v[22:23]
	v_mul_f32_e32 v0, 0xbfb8aa3b, v30
	v_mul_f32_e32 v32, 0xbfb8aa3b, v31
	v_exp_f32_e32 v0, v0
	v_exp_f32_e32 v32, v32
	s_waitcnt vmcnt(0)
	v_pk_fma_f32 v[28:29], v[66:67], v[28:29], v[78:79]
	v_mul_f32_e32 v24, 0xbfb8aa3b, v23
	v_add_f32_e32 v0, 1.0, v0
	v_add_f32_e32 v33, 1.0, v32
	v_rcp_f32_e32 v32, v0
	v_rcp_f32_e32 v33, v33
	v_mul_f32_e32 v0, 0xbfb8aa3b, v22
	v_exp_f32_e32 v0, v0
	v_pk_fma_f32 v[26:27], v[70:71], v[26:27], v[28:29]
	v_pk_mul_f32 v[28:29], v[30:31], v[32:33]
	v_exp_f32_e32 v30, v24
	v_pk_fma_f32 v[26:27], v[10:11], v[74:75], v[26:27]
	v_add_f32_e32 v0, 1.0, v0
	v_pk_mul_f32 v[24:25], v[26:27], v[28:29]
	v_rcp_f32_e32 v26, v0
	v_add_f32_e32 v0, 1.0, v30
	v_rcp_f32_e32 v27, v0
	v_pk_fma_f32 v[20:21], v[68:69], v[20:21], v[80:81]
	s_nop 0
	v_pk_fma_f32 v[18:19], v[72:73], v[18:19], v[20:21]
	v_pk_mul_f32 v[20:21], v[22:23], v[26:27]
	v_pk_fma_f32 v[18:19], v[12:13], v[76:77], v[18:19]
	s_nop 0
	v_pk_mul_f32 v[18:19], v[18:19], v[20:21]
	v_cvt_pk_bf16_f32 v20, v24, v25
	v_cvt_pk_bf16_f32 v21, v18, v19
	v_mov_b64_e32 v[18:19], s[12:13]
	v_mad_u64_u32 v[18:19], s[18:19], v110, s60, v[18:19]
	v_mad_i32_i24 v19, v111, s60, v19
	v_lshl_add_u64 v[18:19], v[202:203], 1, v[18:19]
	global_store_dwordx2 v[18:19], v[20:21], off offset:8
.LBB0_728:
	s_or_b64 exec, exec, s[16:17]
	v_cndmask_b32_e64 v0, v6, v14, s[42:43]
	v_cndmask_b32_e64 v244, v6, v14, s[40:41]
	v_cndmask_b32_e64 v245, v2, v10, s[42:43]
	v_mov_b32_dpp v22, v0 row_ror:1 row_mask:0xf bank_mask:0xf
	v_mov_b32_dpp v24, v244 row_ror:2 row_mask:0xf bank_mask:0xf
	v_mov_b32_dpp v18, v245 row_ror:1 row_mask:0xf bank_mask:0xf
	v_cndmask_b32_e64 v0, v2, v10, s[40:41]
	v_cndmask_b32_e64 v244, v7, v15, s[42:43]
	v_cndmask_b32_e64 v245, v7, v15, s[40:41]
	v_mov_b32_dpp v20, v0 row_ror:2 row_mask:0xf bank_mask:0xf
	v_mov_b32_dpp v23, v244 row_ror:1 row_mask:0xf bank_mask:0xf
	v_mov_b32_dpp v25, v245 row_ror:2 row_mask:0xf bank_mask:0xf
	v_cndmask_b32_e64 v0, v3, v11, s[42:43]
	v_cndmask_b32_e64 v244, v3, v11, s[40:41]
	v_cndmask_b32_e64 v245, v8, v16, s[42:43]
	v_mov_b32_dpp v19, v0 row_ror:1 row_mask:0xf bank_mask:0xf
	v_mov_b32_dpp v21, v244 row_ror:2 row_mask:0xf bank_mask:0xf
	v_mov_b32_dpp v14, v245 row_ror:1 row_mask:0xf bank_mask:0xf
	v_cndmask_b32_e64 v0, v8, v16, s[40:41]
	v_cndmask_b32_e64 v244, v4, v12, s[42:43]
	v_cndmask_b32_e64 v245, v4, v12, s[40:41]
	v_mov_b32_dpp v16, v0 row_ror:2 row_mask:0xf bank_mask:0xf
	v_mov_b32_dpp v10, v244 row_ror:1 row_mask:0xf bank_mask:0xf
	v_mov_b32_dpp v12, v245 row_ror:2 row_mask:0xf bank_mask:0xf
	v_cndmask_b32_e64 v0, v9, v17, s[42:43]
	v_cndmask_b32_e64 v244, v9, v17, s[40:41]
	v_cndmask_b32_e64 v245, v5, v13, s[42:43]
	v_mov_b32_dpp v15, v0 row_ror:1 row_mask:0xf bank_mask:0xf
	v_mov_b32_dpp v17, v244 row_ror:2 row_mask:0xf bank_mask:0xf
	v_mov_b32_dpp v11, v245 row_ror:1 row_mask:0xf bank_mask:0xf
	v_cndmask_b32_e64 v0, v5, v13, s[40:41]
	s_nop 1
	v_mov_b32_dpp v13, v0 row_ror:2 row_mask:0xf bank_mask:0xf
	s_and_saveexec_b64 s[16:17], s[52:53]
	s_cbranch_execz .LBB0_730
	s_waitcnt vmcnt(4)
	v_pk_fma_f32 v[24:25], v[82:83], v[24:25], v[94:95]
	v_pk_fma_f32 v[16:17], v[84:85], v[16:17], v[96:97]
	v_pk_fma_f32 v[22:23], v[86:87], v[22:23], v[24:25]
	v_pk_fma_f32 v[14:15], v[88:89], v[14:15], v[16:17]
	v_pk_fma_f32 v[6:7], v[6:7], v[90:91], v[22:23]
	v_pk_fma_f32 v[8:9], v[8:9], v[92:93], v[14:15]
	v_mul_f32_e32 v0, 0xbfb8aa3b, v6
	v_exp_f32_e32 v0, v0
	v_mul_f32_e32 v22, 0xbfb8aa3b, v7
	v_exp_f32_e32 v22, v22
	v_mul_f32_e32 v14, 0xbfb8aa3b, v9
	v_add_f32_e32 v0, 1.0, v0
	v_exp_f32_e32 v14, v14
	v_add_f32_e32 v23, 1.0, v22
	v_rcp_f32_e32 v22, v0
	v_mul_f32_e32 v0, 0xbfb8aa3b, v8
	v_rcp_f32_e32 v23, v23
	v_exp_f32_e32 v0, v0
	s_waitcnt vmcnt(0)
	v_pk_fma_f32 v[20:21], v[66:67], v[20:21], v[78:79]
	v_pk_fma_f32 v[12:13], v[68:69], v[12:13], v[80:81]
	v_pk_fma_f32 v[18:19], v[70:71], v[18:19], v[20:21]
	v_pk_mul_f32 v[6:7], v[6:7], v[22:23]
	v_pk_fma_f32 v[2:3], v[2:3], v[74:75], v[18:19]
	v_add_f32_e32 v0, 1.0, v0
	v_pk_mul_f32 v[2:3], v[2:3], v[6:7]
	v_rcp_f32_e32 v6, v0
	v_add_f32_e32 v0, 1.0, v14
	v_rcp_f32_e32 v7, v0
	v_pk_fma_f32 v[10:11], v[72:73], v[10:11], v[12:13]
	v_cvt_pk_bf16_f32 v2, v2, v3
	v_pk_fma_f32 v[4:5], v[4:5], v[76:77], v[10:11]
	v_pk_mul_f32 v[6:7], v[8:9], v[6:7]
	s_nop 0
	v_pk_mul_f32 v[4:5], v[4:5], v[6:7]
	s_nop 0
	v_cvt_pk_bf16_f32 v3, v4, v5
	v_mov_b64_e32 v[4:5], s[12:13]
	v_mad_u64_u32 v[4:5], s[18:19], v148, s60, v[4:5]
	v_mad_i32_i24 v5, v149, s60, v5
	v_lshl_add_u64 v[4:5], v[202:203], 1, v[4:5]
	global_store_dwordx2 v[4:5], v[2:3], off offset:8

; __global__ void __launch_bounds__(512) mega_fwd(Params p) {
	.amdhsa_kernel _Z8mega_fwd6Params
		.amdhsa_group_segment_fixed_size 0
		.amdhsa_private_segment_fixed_size 0
		.amdhsa_kernarg_size 448
		.amdhsa_user_sgpr_count 2
		.amdhsa_user_sgpr_dispatch_ptr 0
		.amdhsa_user_sgpr_queue_ptr 0
		.amdhsa_user_sgpr_kernarg_segment_ptr 1
		.amdhsa_user_sgpr_dispatch_id 0
		.amdhsa_user_sgpr_kernarg_preload_length 0
		.amdhsa_user_sgpr_kernarg_preload_offset 0
		.amdhsa_user_sgpr_private_segment_size 0
		.amdhsa_uses_dynamic_stack 0
		.amdhsa_enable_private_segment 0
		.amdhsa_system_sgpr_workgroup_id_x 1
		.amdhsa_system_sgpr_workgroup_id_y 0
		.amdhsa_system_sgpr_workgroup_id_z 0
		.amdhsa_system_sgpr_workgroup_info 0
		.amdhsa_system_vgpr_workitem_id 2
		.amdhsa_next_free_vgpr 256
		.amdhsa_next_free_sgpr 100
		.amdhsa_accum_offset 256
		.amdhsa_reserve_vcc 1
		.amdhsa_float_round_mode_32 0
		.amdhsa_float_round_mode_16_64 0
		.amdhsa_float_denorm_mode_32 3
		.amdhsa_float_denorm_mode_16_64 3
		.amdhsa_dx10_clamp 1
		.amdhsa_ieee_mode 1
		.amdhsa_fp16_overflow 0
		.amdhsa_tg_split 0
		.amdhsa_exception_fp_ieee_invalid_op 0
		.amdhsa_exception_fp_denorm_src 0
		.amdhsa_exception_fp_ieee_div_zero 0
		.amdhsa_exception_fp_ieee_overflow 0
		.amdhsa_exception_fp_ieee_underflow 0
		.amdhsa_exception_fp_ieee_inexact 0
		.amdhsa_exception_int_div_zero 0
	.end_amdhsa_kernel

; __global__ void __launch_bounds__(512) mega_fwd(Params p) {
amdhsa.kernels:
  - .agpr_count:     0
    .args:
      - .offset:         0
        .size:           192
        .value_kind:     by_value
      - .offset:         192
        .size:           4
        .value_kind:     hidden_block_count_x
      - .offset:         196
        .size:           4
        .value_kind:     hidden_block_count_y
      - .offset:         200
        .size:           4
        .value_kind:     hidden_block_count_z
      - .offset:         204
        .size:           2
        .value_kind:     hidden_group_size_x
      - .offset:         206
        .size:           2
        .value_kind:     hidden_group_size_y
      - .offset:         208
        .size:           2
        .value_kind:     hidden_group_size_z
      - .offset:         210
        .size:           2
        .value_kind:     hidden_remainder_x
      - .offset:         212
        .size:           2
        .value_kind:     hidden_remainder_y
      - .offset:         214
        .size:           2
        .value_kind:     hidden_remainder_z
      - .offset:         232
        .size:           8
        .value_kind:     hidden_global_offset_x
      - .offset:         240
        .size:           8
        .value_kind:     hidden_global_offset_y
      - .offset:         248
        .size:           8
        .value_kind:     hidden_global_offset_z
      - .offset:         256
        .size:           2
        .value_kind:     hidden_grid_dims
      - .offset:         280
        .size:           8
        .value_kind:     hidden_multigrid_sync_arg
      - .offset:         312
        .size:           4
        .value_kind:     hidden_dynamic_lds_size
    .group_segment_fixed_size: 0
    .kernarg_segment_align: 8
    .kernarg_segment_size: 448
    .language:       OpenCL C
    .language_version:
      - 2
      - 0
    .max_flat_workgroup_size: 512
    .name:           _Z8mega_fwd6Params
    .private_segment_fixed_size: 0
    .sgpr_count:     106
    .sgpr_spill_count: 229
    .symbol:         _Z8mega_fwd6Params.kd
    .uniform_work_group_size: 1
    .uses_dynamic_stack: false
    .vgpr_count:     256
    .vgpr_spill_count: 0
    .wavefront_size: 64
